# E23: P1a EpiZ int8 per-column scale words staged by LDS-DMA at the unit head into the unused EPI_H scratch; epilogue reads them with ds_read_b128 instead of 4 serial global loads
# baseline (speedup 1.0000x reference)
.LBB0_224:
	s_ashr_i32 s45, s44, 31
	s_lshl_b64 s[20:21], s[44:45], 20
	v_readlane_b32 s14, v250, 4
	v_readlane_b32 s15, v250, 5
	s_add_u32 s34, s14, s20
	s_addc_u32 s35, s15, s21
	s_and_b64 s[20:21], s[2:3], exec
	s_cselect_b32 s5, s35, s79
	s_cselect_b32 s14, s34, s78
	s_ashr_i32 s85, s84, 31
	s_lshl_b64 s[20:21], s[84:85], 20
	s_add_u32 s70, s90, s20
	s_addc_u32 s71, s91, s21
	s_and_b64 s[20:21], s[2:3], exec
	s_cselect_b32 s20, s71, s23
	s_cselect_b32 s21, s70, s22
	s_add_u32 s24, s22, 0x100
	s_addc_u32 s45, s23, 0
	s_add_u32 s22, s78, 0x80080
	v_mov_b32_e32 v124, 0
	s_addc_u32 s23, s79, 0
	s_mov_b32 s78, -2
	v_mov_b32_e32 v125, v124
	v_mov_b32_e32 v126, v124
	v_mov_b32_e32 v127, v124
	v_mov_b32_e32 v92, v124
	v_mov_b32_e32 v93, v124
	v_mov_b32_e32 v94, v124
	v_mov_b32_e32 v95, v124
	v_mov_b32_e32 v96, v124
	v_mov_b32_e32 v97, v124
	v_mov_b32_e32 v98, v124
	v_mov_b32_e32 v99, v124
	v_mov_b32_e32 v64, v124
	v_mov_b32_e32 v65, v124
	v_mov_b32_e32 v66, v124
	v_mov_b32_e32 v67, v124
	v_mov_b32_e32 v100, v124
	v_mov_b32_e32 v101, v124
	v_mov_b32_e32 v102, v124
	v_mov_b32_e32 v103, v124
	v_mov_b32_e32 v68, v124
	v_mov_b32_e32 v69, v124
	v_mov_b32_e32 v70, v124
	v_mov_b32_e32 v71, v124
	v_mov_b32_e32 v104, v124
	v_mov_b32_e32 v105, v124
	v_mov_b32_e32 v106, v124
	v_mov_b32_e32 v107, v124
	v_mov_b32_e32 v72, v124
	v_mov_b32_e32 v73, v124
	v_mov_b32_e32 v74, v124
	v_mov_b32_e32 v75, v124
	v_mov_b32_e32 v60, v124
	v_mov_b32_e32 v61, v124
	v_mov_b32_e32 v62, v124
	v_mov_b32_e32 v63, v124
	v_mov_b32_e32 v28, v124
	v_mov_b32_e32 v29, v124
	v_mov_b32_e32 v30, v124
	v_mov_b32_e32 v31, v124
	v_mov_b32_e32 v32, v124
	v_mov_b32_e32 v33, v124
	v_mov_b32_e32 v34, v124
	v_mov_b32_e32 v35, v124
	v_mov_b32_e32 v24, v124
	v_mov_b32_e32 v25, v124
	v_mov_b32_e32 v26, v124
	v_mov_b32_e32 v27, v124
	v_mov_b32_e32 v36, v124
	v_mov_b32_e32 v37, v124
	v_mov_b32_e32 v38, v124
	v_mov_b32_e32 v39, v124
	v_mov_b32_e32 v16, v124
	v_mov_b32_e32 v17, v124
	v_mov_b32_e32 v18, v124
	v_mov_b32_e32 v19, v124
	v_mov_b32_e32 v40, v124
	v_mov_b32_e32 v41, v124
	v_mov_b32_e32 v42, v124
	v_mov_b32_e32 v43, v124
	v_mov_b32_e32 v20, v124
	v_mov_b32_e32 v21, v124
	v_mov_b32_e32 v22, v124
	v_mov_b32_e32 v23, v124
	v_mov_b32_e32 v108, v124
	v_mov_b32_e32 v109, v124
	v_mov_b32_e32 v110, v124
	v_mov_b32_e32 v111, v124
	v_mov_b32_e32 v76, v124
	v_mov_b32_e32 v77, v124
	v_mov_b32_e32 v78, v124
	v_mov_b32_e32 v79, v124
	v_mov_b32_e32 v112, v124
	v_mov_b32_e32 v113, v124
	v_mov_b32_e32 v114, v124
	v_mov_b32_e32 v115, v124
	v_mov_b32_e32 v80, v124
	v_mov_b32_e32 v81, v124
	v_mov_b32_e32 v82, v124
	v_mov_b32_e32 v83, v124
	v_mov_b32_e32 v116, v124
	v_mov_b32_e32 v117, v124
	v_mov_b32_e32 v118, v124
	v_mov_b32_e32 v119, v124
	v_mov_b32_e32 v84, v124
	v_mov_b32_e32 v85, v124
	v_mov_b32_e32 v86, v124
	v_mov_b32_e32 v87, v124
	v_mov_b32_e32 v120, v124
	v_mov_b32_e32 v121, v124
	v_mov_b32_e32 v122, v124
	v_mov_b32_e32 v123, v124
	v_mov_b32_e32 v88, v124
	v_mov_b32_e32 v89, v124
	v_mov_b32_e32 v90, v124
	v_mov_b32_e32 v91, v124
	v_mov_b32_e32 v44, v124
	v_mov_b32_e32 v45, v124
	v_mov_b32_e32 v46, v124
	v_mov_b32_e32 v47, v124
	v_mov_b32_e32 v8, v124
	v_mov_b32_e32 v9, v124
	v_mov_b32_e32 v10, v124
	v_mov_b32_e32 v11, v124
	v_mov_b32_e32 v48, v124
	v_mov_b32_e32 v49, v124
	v_mov_b32_e32 v50, v124
	v_mov_b32_e32 v51, v124
	v_mov_b32_e32 v12, v124
	v_mov_b32_e32 v13, v124
	v_mov_b32_e32 v14, v124
	v_mov_b32_e32 v15, v124
	v_mov_b32_e32 v52, v124
	v_mov_b32_e32 v53, v124
	v_mov_b32_e32 v54, v124
	v_mov_b32_e32 v55, v124
	v_mov_b32_e32 v4, v124
	v_mov_b32_e32 v5, v124
	v_mov_b32_e32 v6, v124
	v_mov_b32_e32 v7, v124
	v_mov_b32_e32 v56, v124
	v_mov_b32_e32 v57, v124
	v_mov_b32_e32 v58, v124
	v_mov_b32_e32 v59, v124
	v_mov_b32_e32 v0, v124
	v_mov_b32_e32 v1, v124
	v_mov_b32_e32 v2, v124
	v_mov_b32_e32 v3, v124
	v_readlane_b32 s98, v251, 42
	s_cmp_lt_u32 s98, 4
	s_cbranch_scc0 .Lcm1_skip
	v_mbcnt_lo_u32_b32 v230, -1, 0
	v_mbcnt_hi_u32_b32 v230, -1, v230
	v_lshlrev_b32_e32 v230, 2, v230
	s_lshl_b32 s99, s4, 10
	s_lshl_b32 s100, s98, 8
	s_add_i32 s99, s99, s100
	v_readlane_b32 s100, v251, 19
	v_readlane_b32 s101, v251, 20
	s_add_u32 s100, s100, 0x60000
	s_addc_u32 s101, s101, 0
	s_add_u32 s100, s100, s99
	s_addc_u32 s101, s101, 0
	s_lshl_b32 s99, s98, 8
	s_add_i32 m0, s99, 0x22000
	s_nop 0
	global_load_lds_dword v230, s[100:101]
.Lcm1_skip:
.LBB0_225:
	ds_read_b128 v[128:131], v157
	ds_read_b128 v[132:135], v157 offset:1024
	ds_read_b128 v[146:149], v157 offset:2048
	ds_read_b128 v[164:167], v157 offset:3072
	ds_read_b128 v[168:171], v159
	ds_read_b128 v[172:175], v159 offset:1024
	ds_read_b128 v[176:179], v159 offset:2048
	ds_read_b128 v[180:183], v159 offset:3072
	s_add_u32 s36, s22, 0xfff80080
	s_addc_u32 s37, s23, -1
	s_cmp_eq_u32 s78, 28
	s_cselect_b32 s81, s5, s37
	s_cselect_b32 s80, s14, s36
	s_cselect_b32 vcc_hi, s20, s45
	s_cselect_b32 vcc_lo, s21, s24
	s_add_i32 m0, s77, 0xc000
	ds_read_b128 v[184:187], v161
	ds_read_b128 v[188:191], v161 offset:1024
	ds_read_b128 v[192:195], v161 offset:2048
	ds_read_b128 v[196:199], v161 offset:3072
	ds_read_b128 v[200:203], v161 offset:4096
	ds_read_b128 v[204:207], v161 offset:5120
	ds_read_b128 v[208:211], v161 offset:6144
	ds_read_b128 v[212:215], v161 offset:7168
	global_load_lds_dwordx4 v140, s[22:23]
	s_add_i32 m0, s77, 0xe000
	s_nop 0
	s_add_u32 s98, s22, s6
	s_addc_u32 s99, s23, s7
	global_load_lds_dwordx4 v140, s[98:99]
	s_waitcnt vmcnt(8)
	s_waitcnt lgkmcnt(0)
	s_barrier
	s_setprio 1
	s_waitcnt lgkmcnt(0)
	v_mfma_i32_16x16x64_i8 v[0:3], v[128:131], v[184:187], v[0:3]
	v_mfma_i32_16x16x64_i8 v[0:3], v[132:135], v[188:191], v[0:3]
	v_mfma_i32_16x16x64_i8 v[56:59], v[146:149], v[184:187], v[56:59]
	v_mfma_i32_16x16x64_i8 v[56:59], v[164:167], v[188:191], v[56:59]
	v_mfma_i32_16x16x64_i8 v[4:7], v[128:131], v[192:195], v[4:7]
	v_mfma_i32_16x16x64_i8 v[4:7], v[132:135], v[196:199], v[4:7]
	v_mfma_i32_16x16x64_i8 v[52:55], v[146:149], v[192:195], v[52:55]
	v_mfma_i32_16x16x64_i8 v[52:55], v[164:167], v[196:199], v[52:55]
	v_mfma_i32_16x16x64_i8 v[12:15], v[128:131], v[200:203], v[12:15]
	v_mfma_i32_16x16x64_i8 v[12:15], v[132:135], v[204:207], v[12:15]
	v_mfma_i32_16x16x64_i8 v[48:51], v[146:149], v[200:203], v[48:51]
	v_mfma_i32_16x16x64_i8 v[48:51], v[164:167], v[204:207], v[48:51]
	v_mfma_i32_16x16x64_i8 v[8:11], v[128:131], v[208:211], v[8:11]
	v_mfma_i32_16x16x64_i8 v[8:11], v[132:135], v[212:215], v[8:11]
	v_mfma_i32_16x16x64_i8 v[44:47], v[146:149], v[208:211], v[44:47]
	v_mfma_i32_16x16x64_i8 v[44:47], v[164:167], v[212:215], v[44:47]
	s_setprio 0
	s_setprio 1
	v_mfma_i32_16x16x64_i8 v[88:91], v[168:171], v[184:187], v[88:91]
	v_mfma_i32_16x16x64_i8 v[88:91], v[172:175], v[188:191], v[88:91]
	v_mfma_i32_16x16x64_i8 v[120:123], v[176:179], v[184:187], v[120:123]
	v_mfma_i32_16x16x64_i8 v[120:123], v[180:183], v[188:191], v[120:123]
	v_mfma_i32_16x16x64_i8 v[84:87], v[168:171], v[192:195], v[84:87]
	v_mfma_i32_16x16x64_i8 v[84:87], v[172:175], v[196:199], v[84:87]
	v_mfma_i32_16x16x64_i8 v[116:119], v[176:179], v[192:195], v[116:119]
	v_mfma_i32_16x16x64_i8 v[116:119], v[180:183], v[196:199], v[116:119]
	v_mfma_i32_16x16x64_i8 v[80:83], v[168:171], v[200:203], v[80:83]
	v_mfma_i32_16x16x64_i8 v[80:83], v[172:175], v[204:207], v[80:83]
	v_mfma_i32_16x16x64_i8 v[112:115], v[176:179], v[200:203], v[112:115]
	v_mfma_i32_16x16x64_i8 v[112:115], v[180:183], v[204:207], v[112:115]
	s_setprio 2
	s_barrier
	v_mfma_i32_16x16x64_i8 v[76:79], v[168:171], v[208:211], v[76:79]
	v_mfma_i32_16x16x64_i8 v[76:79], v[172:175], v[212:215], v[76:79]
	v_mfma_i32_16x16x64_i8 v[108:111], v[176:179], v[208:211], v[108:111]
	v_mfma_i32_16x16x64_i8 v[108:111], v[180:183], v[212:215], v[108:111]
	s_setprio 0
	s_add_i32 s36, s86, s63
	s_mov_b32 m0, s36
	ds_read_b128 v[184:187], v161 offset:16384
	ds_read_b128 v[188:191], v161 offset:17408
	ds_read_b128 v[192:195], v161 offset:18432
	ds_read_b128 v[196:199], v161 offset:19456
	ds_read_b128 v[200:203], v161 offset:20480
	ds_read_b128 v[204:207], v161 offset:21504
	ds_read_b128 v[208:211], v161 offset:22528
	ds_read_b128 v[212:215], v161 offset:23552
	global_load_lds_dwordx4 v138, vcc
	s_add_i32 m0, s36, 0x2000
	s_add_i32 s36, s87, s63
	s_add_u32 s98, vcc_lo, s6
	s_addc_u32 s99, vcc_hi, s7
	global_load_lds_dwordx4 v138, s[98:99]
	s_mov_b32 m0, s36
	s_nop 0
	s_add_u32 s98, vcc_lo, s8
	s_addc_u32 s99, vcc_hi, s9
	global_load_lds_dwordx4 v138, s[98:99]
	s_add_i32 m0, s36, 0x2000
	s_nop 0
	s_add_u32 s98, vcc_lo, s10
	s_addc_u32 s99, vcc_hi, s11
	global_load_lds_dwordx4 v138, s[98:99]
	s_mov_b32 m0, s77
	s_nop 0
	global_load_lds_dwordx4 v136, s[80:81]
	s_mov_b32 m0, s97
	s_nop 0
	s_add_u32 s98, s80, s6
	s_addc_u32 s99, s81, s7
	global_load_lds_dwordx4 v136, s[98:99]
	s_waitcnt vmcnt(8)
	s_waitcnt lgkmcnt(0)
	s_barrier
	s_setprio 1
	s_waitcnt lgkmcnt(0)
	v_mfma_i32_16x16x64_i8 v[20:23], v[128:131], v[184:187], v[20:23]
	v_mfma_i32_16x16x64_i8 v[20:23], v[132:135], v[188:191], v[20:23]
	v_mfma_i32_16x16x64_i8 v[40:43], v[146:149], v[184:187], v[40:43]
	v_mfma_i32_16x16x64_i8 v[40:43], v[164:167], v[188:191], v[40:43]
	v_mfma_i32_16x16x64_i8 v[16:19], v[128:131], v[192:195], v[16:19]
	v_mfma_i32_16x16x64_i8 v[16:19], v[132:135], v[196:199], v[16:19]
	v_mfma_i32_16x16x64_i8 v[36:39], v[146:149], v[192:195], v[36:39]
	v_mfma_i32_16x16x64_i8 v[36:39], v[164:167], v[196:199], v[36:39]
	v_mfma_i32_16x16x64_i8 v[24:27], v[128:131], v[200:203], v[24:27]
	v_mfma_i32_16x16x64_i8 v[24:27], v[132:135], v[204:207], v[24:27]
	v_mfma_i32_16x16x64_i8 v[32:35], v[146:149], v[200:203], v[32:35]
	v_mfma_i32_16x16x64_i8 v[32:35], v[164:167], v[204:207], v[32:35]
	v_mfma_i32_16x16x64_i8 v[28:31], v[128:131], v[208:211], v[28:31]
	v_mfma_i32_16x16x64_i8 v[28:31], v[132:135], v[212:215], v[28:31]
	v_mfma_i32_16x16x64_i8 v[60:63], v[146:149], v[208:211], v[60:63]
	v_mfma_i32_16x16x64_i8 v[60:63], v[164:167], v[212:215], v[60:63]
	s_setprio 0
	s_setprio 1
	v_mfma_i32_16x16x64_i8 v[72:75], v[168:171], v[184:187], v[72:75]
	v_mfma_i32_16x16x64_i8 v[72:75], v[172:175], v[188:191], v[72:75]
	v_mfma_i32_16x16x64_i8 v[104:107], v[176:179], v[184:187], v[104:107]
	v_mfma_i32_16x16x64_i8 v[104:107], v[180:183], v[188:191], v[104:107]
	v_mfma_i32_16x16x64_i8 v[68:71], v[168:171], v[192:195], v[68:71]
	v_mfma_i32_16x16x64_i8 v[68:71], v[172:175], v[196:199], v[68:71]
	v_mfma_i32_16x16x64_i8 v[100:103], v[176:179], v[192:195], v[100:103]
	v_mfma_i32_16x16x64_i8 v[100:103], v[180:183], v[196:199], v[100:103]
	v_mfma_i32_16x16x64_i8 v[64:67], v[168:171], v[200:203], v[64:67]
	v_mfma_i32_16x16x64_i8 v[64:67], v[172:175], v[204:207], v[64:67]
	v_mfma_i32_16x16x64_i8 v[96:99], v[176:179], v[200:203], v[96:99]
	v_mfma_i32_16x16x64_i8 v[96:99], v[180:183], v[204:207], v[96:99]
	s_setprio 2
	s_barrier
	v_mfma_i32_16x16x64_i8 v[92:95], v[168:171], v[208:211], v[92:95]
	v_mfma_i32_16x16x64_i8 v[92:95], v[172:175], v[212:215], v[92:95]
	v_mfma_i32_16x16x64_i8 v[124:127], v[176:179], v[208:211], v[124:127]
	v_mfma_i32_16x16x64_i8 v[124:127], v[180:183], v[212:215], v[124:127]
	s_setprio 0
	s_add_i32 s36, 0, 0x18000
	v_add_u32_e32 v152, s36, v153
	s_add_i32 s37, 0, 0x1c000
	ds_read_b128 v[128:131], v152
	ds_read_b128 v[132:135], v152 offset:1024
	ds_read_b128 v[146:149], v152 offset:2048
	ds_read_b128 v[164:167], v152 offset:3072
	v_add_u32_e32 v152, s37, v153
	ds_read_b128 v[168:171], v152
	ds_read_b128 v[172:175], v152 offset:1024
	ds_read_b128 v[176:179], v152 offset:2048
	ds_read_b128 v[180:183], v152 offset:3072
	s_mov_b32 m0, s33
	ds_read_b128 v[184:187], v161 offset:32768
	ds_read_b128 v[188:191], v161 offset:33792
	ds_read_b128 v[192:195], v161 offset:34816
	ds_read_b128 v[196:199], v161 offset:35840
	ds_read_b128 v[200:203], v161 offset:36864
	ds_read_b128 v[204:207], v161 offset:37888
	ds_read_b128 v[208:211], v161 offset:38912
	ds_read_b128 v[212:215], v161 offset:39936
	s_add_u32 s98, s80, s8
	s_addc_u32 s99, s81, s9
	global_load_lds_dwordx4 v136, s[98:99]
	s_mov_b32 m0, s93
	s_nop 0
	s_add_u32 s98, s80, s10
	s_addc_u32 s99, s81, s11
	global_load_lds_dwordx4 v136, s[98:99]
	s_waitcnt vmcnt(8)
	s_waitcnt lgkmcnt(0)
	s_barrier
	s_setprio 1
	s_waitcnt lgkmcnt(0)
	v_mfma_i32_16x16x64_i8 v[0:3], v[128:131], v[184:187], v[0:3]
	v_mfma_i32_16x16x64_i8 v[0:3], v[132:135], v[188:191], v[0:3]
	v_mfma_i32_16x16x64_i8 v[56:59], v[146:149], v[184:187], v[56:59]
	v_mfma_i32_16x16x64_i8 v[56:59], v[164:167], v[188:191], v[56:59]
	v_mfma_i32_16x16x64_i8 v[4:7], v[128:131], v[192:195], v[4:7]
	v_mfma_i32_16x16x64_i8 v[4:7], v[132:135], v[196:199], v[4:7]
	v_mfma_i32_16x16x64_i8 v[52:55], v[146:149], v[192:195], v[52:55]
	v_mfma_i32_16x16x64_i8 v[52:55], v[164:167], v[196:199], v[52:55]
	v_mfma_i32_16x16x64_i8 v[12:15], v[128:131], v[200:203], v[12:15]
	v_mfma_i32_16x16x64_i8 v[12:15], v[132:135], v[204:207], v[12:15]
	v_mfma_i32_16x16x64_i8 v[48:51], v[146:149], v[200:203], v[48:51]
	v_mfma_i32_16x16x64_i8 v[48:51], v[164:167], v[204:207], v[48:51]
	v_mfma_i32_16x16x64_i8 v[8:11], v[128:131], v[208:211], v[8:11]
	v_mfma_i32_16x16x64_i8 v[8:11], v[132:135], v[212:215], v[8:11]
	v_mfma_i32_16x16x64_i8 v[44:47], v[146:149], v[208:211], v[44:47]
	v_mfma_i32_16x16x64_i8 v[44:47], v[164:167], v[212:215], v[44:47]
	s_setprio 0
	s_setprio 1
	v_mfma_i32_16x16x64_i8 v[88:91], v[168:171], v[184:187], v[88:91]
	v_mfma_i32_16x16x64_i8 v[88:91], v[172:175], v[188:191], v[88:91]
	v_mfma_i32_16x16x64_i8 v[120:123], v[176:179], v[184:187], v[120:123]
	v_mfma_i32_16x16x64_i8 v[120:123], v[180:183], v[188:191], v[120:123]
	v_mfma_i32_16x16x64_i8 v[84:87], v[168:171], v[192:195], v[84:87]
	v_mfma_i32_16x16x64_i8 v[84:87], v[172:175], v[196:199], v[84:87]
	v_mfma_i32_16x16x64_i8 v[116:119], v[176:179], v[192:195], v[116:119]
	v_mfma_i32_16x16x64_i8 v[116:119], v[180:183], v[196:199], v[116:119]
	v_mfma_i32_16x16x64_i8 v[80:83], v[168:171], v[200:203], v[80:83]
	v_mfma_i32_16x16x64_i8 v[80:83], v[172:175], v[204:207], v[80:83]
	v_mfma_i32_16x16x64_i8 v[112:115], v[176:179], v[200:203], v[112:115]
	v_mfma_i32_16x16x64_i8 v[112:115], v[180:183], v[204:207], v[112:115]
	s_setprio 2
	s_barrier
	v_mfma_i32_16x16x64_i8 v[76:79], v[168:171], v[208:211], v[76:79]
	v_mfma_i32_16x16x64_i8 v[76:79], v[172:175], v[212:215], v[76:79]
	v_mfma_i32_16x16x64_i8 v[108:111], v[176:179], v[208:211], v[108:111]
	v_mfma_i32_16x16x64_i8 v[108:111], v[180:183], v[212:215], v[108:111]
	s_setprio 0
	s_add_i32 s36, s36, s63
	s_mov_b32 m0, s36
	ds_read_b128 v[184:187], v161 offset:49152
	ds_read_b128 v[188:191], v161 offset:50176
	ds_read_b128 v[192:195], v161 offset:51200
	ds_read_b128 v[196:199], v161 offset:52224
	ds_read_b128 v[200:203], v161 offset:53248
	ds_read_b128 v[204:207], v161 offset:54272
	ds_read_b128 v[208:211], v161 offset:55296
	ds_read_b128 v[212:215], v161 offset:56320
	s_add_u32 s98, vcc_lo, s46
	s_addc_u32 s99, vcc_hi, s47
	global_load_lds_dwordx4 v138, s[98:99]
	s_add_i32 m0, s36, 0x2000
	s_add_i32 s36, s37, s63
	s_add_u32 s98, vcc_lo, s48
	s_addc_u32 s99, vcc_hi, s49
	global_load_lds_dwordx4 v138, s[98:99]
	s_mov_b32 m0, s36
	s_add_u32 s98, vcc_lo, s54
	s_addc_u32 s99, vcc_hi, s55
	global_load_lds_dwordx4 v138, s[98:99]
	s_add_i32 m0, s36, 0x2000
	s_nop 0
	s_add_u32 s98, vcc_lo, s56
	s_addc_u32 s99, vcc_hi, s57
	global_load_lds_dwordx4 v138, s[98:99]
	s_mov_b32 m0, s95
	s_nop 0
	s_add_u32 s98, s80, s46
	s_addc_u32 s99, s81, s47
	global_load_lds_dwordx4 v136, s[98:99]
	s_mov_b32 m0, s82
	s_nop 0
	s_add_u32 s98, s80, s48
	s_addc_u32 s99, s81, s49
	global_load_lds_dwordx4 v136, s[98:99]
	s_waitcnt vmcnt(8)
	s_waitcnt lgkmcnt(0)
	s_barrier
	s_setprio 1
	s_waitcnt lgkmcnt(0)
	v_mfma_i32_16x16x64_i8 v[20:23], v[128:131], v[184:187], v[20:23]
	v_mfma_i32_16x16x64_i8 v[20:23], v[132:135], v[188:191], v[20:23]
	v_mfma_i32_16x16x64_i8 v[40:43], v[146:149], v[184:187], v[40:43]
	v_mfma_i32_16x16x64_i8 v[40:43], v[164:167], v[188:191], v[40:43]
	v_mfma_i32_16x16x64_i8 v[16:19], v[128:131], v[192:195], v[16:19]
	v_mfma_i32_16x16x64_i8 v[16:19], v[132:135], v[196:199], v[16:19]
	v_mfma_i32_16x16x64_i8 v[36:39], v[146:149], v[192:195], v[36:39]
	v_mfma_i32_16x16x64_i8 v[36:39], v[164:167], v[196:199], v[36:39]
	v_mfma_i32_16x16x64_i8 v[24:27], v[128:131], v[200:203], v[24:27]
	v_mfma_i32_16x16x64_i8 v[24:27], v[132:135], v[204:207], v[24:27]
	v_mfma_i32_16x16x64_i8 v[32:35], v[146:149], v[200:203], v[32:35]
	v_mfma_i32_16x16x64_i8 v[32:35], v[164:167], v[204:207], v[32:35]
	v_mfma_i32_16x16x64_i8 v[28:31], v[128:131], v[208:211], v[28:31]
	v_mfma_i32_16x16x64_i8 v[28:31], v[132:135], v[212:215], v[28:31]
	v_mfma_i32_16x16x64_i8 v[60:63], v[146:149], v[208:211], v[60:63]
	v_mfma_i32_16x16x64_i8 v[60:63], v[164:167], v[212:215], v[60:63]
	s_setprio 0
	s_setprio 1
	v_mfma_i32_16x16x64_i8 v[72:75], v[168:171], v[184:187], v[72:75]
	v_mfma_i32_16x16x64_i8 v[72:75], v[172:175], v[188:191], v[72:75]
	v_mfma_i32_16x16x64_i8 v[104:107], v[176:179], v[184:187], v[104:107]
	v_mfma_i32_16x16x64_i8 v[104:107], v[180:183], v[188:191], v[104:107]
	v_mfma_i32_16x16x64_i8 v[68:71], v[168:171], v[192:195], v[68:71]
	v_mfma_i32_16x16x64_i8 v[68:71], v[172:175], v[196:199], v[68:71]
	v_mfma_i32_16x16x64_i8 v[100:103], v[176:179], v[192:195], v[100:103]
	v_mfma_i32_16x16x64_i8 v[100:103], v[180:183], v[196:199], v[100:103]
	v_mfma_i32_16x16x64_i8 v[64:67], v[168:171], v[200:203], v[64:67]
	v_mfma_i32_16x16x64_i8 v[64:67], v[172:175], v[204:207], v[64:67]
	v_mfma_i32_16x16x64_i8 v[96:99], v[176:179], v[200:203], v[96:99]
	v_mfma_i32_16x16x64_i8 v[96:99], v[180:183], v[204:207], v[96:99]
	s_setprio 2
	s_barrier
	v_mfma_i32_16x16x64_i8 v[92:95], v[168:171], v[208:211], v[92:95]
	v_mfma_i32_16x16x64_i8 v[92:95], v[172:175], v[212:215], v[92:95]
	v_mfma_i32_16x16x64_i8 v[124:127], v[176:179], v[208:211], v[124:127]
	v_mfma_i32_16x16x64_i8 v[124:127], v[180:183], v[212:215], v[124:127]
	s_setprio 0
	s_add_i32 s78, s78, 2
	s_add_u32 s24, s24, 0x100
	s_addc_u32 s45, s45, 0
	s_add_u32 s22, s22, 0x100
	s_addc_u32 s23, s23, 0
	s_cmp_gt_u32 s78, 29
	s_cbranch_scc0 .LBB0_225
	v_readlane_b32 s14, v250, 9
	v_readlane_b32 s15, v250, 10
	s_and_b64 vcc, exec, s[14:15]
	s_cbranch_vccz .LBB0_228
	s_barrier

.LBB0_232:
	v_and_b32_e32 v163, 15, v164
	s_ashr_i32 s36, s4, 3
	s_lshl_b32 s4, s4, 8
	v_lshl_add_u32 v128, v163, 2, s68
	s_ashr_i32 s5, s4, 31
	ds_read2_b32 v[150:151], v128 offset1:16
	ds_read2_b32 v[148:149], v128 offset0:32 offset1:48
	ds_read2_b32 v[134:135], v128 offset0:128 offset1:144
	ds_read2_b32 v[132:133], v128 offset0:160 offset1:176
	v_ashrrev_i32_e32 v128, 1, v164
	s_lshl_b64 s[20:21], s[4:5], 2
	v_and_b32_e32 v146, -8, v128
	s_add_u32 s20, s69, s20
	v_ashrrev_i32_e32 v147, 31, v146
	s_addc_u32 s21, s1, s21
	v_lshl_add_u64 v[154:155], v[146:147], 2, s[20:21]
	v_readlane_b32 s98, v251, 42
	s_and_b32 s98, s98, 3
	s_lshl_b32 s98, s98, 7
	s_add_i32 s98, s98, 0x22000
	v_lshl_add_u32 v230, v146, 2, s98
	ds_read_b128 v[128:131], v230
	v_cvt_f32_i32_e32 v1, v1
	v_cvt_f32_i32_e32 v0, v0
	v_cvt_f32_i32_e32 v3, v3
	v_cvt_f32_i32_e32 v2, v2
	v_cvt_f32_i32_e32 v5, v5
	v_cvt_f32_i32_e32 v4, v4
	v_cvt_f32_i32_e32 v7, v7
	v_cvt_f32_i32_e32 v6, v6
	v_cvt_f32_i32_e32 v13, v13
	v_cvt_f32_i32_e32 v12, v12
	v_cvt_f32_i32_e32 v15, v15
	v_cvt_f32_i32_e32 v14, v14
	s_waitcnt lgkmcnt(0)
	v_mov_b32_e32 v156, v151
	v_cvt_f32_i32_e32 v9, v9
	v_cvt_f32_i32_e32 v8, v8
	v_cvt_f32_i32_e32 v11, v11
	v_cvt_f32_i32_e32 v10, v10
	v_cvt_f32_i32_e32 v21, v21
	v_cvt_f32_i32_e32 v20, v20
	v_cvt_f32_i32_e32 v23, v23
	v_cvt_f32_i32_e32 v22, v22
	v_mov_b32_e32 v158, v149
	v_cvt_f32_i32_e32 v17, v17
	v_cvt_f32_i32_e32 v16, v16
	v_cvt_f32_i32_e32 v19, v19
	v_cvt_f32_i32_e32 v18, v18
	v_cvt_f32_i32_e32 v25, v25
	v_cvt_f32_i32_e32 v24, v24
	v_cvt_f32_i32_e32 v27, v27
	v_cvt_f32_i32_e32 v26, v26
	v_cvt_f32_i32_e32 v29, v29
	v_cvt_f32_i32_e32 v28, v28
	v_cvt_f32_i32_e32 v31, v31
	v_cvt_f32_i32_e32 v30, v30
	v_mov_b32_e32 v160, v135
	v_mov_b32_e32 v152, v133
	s_waitcnt lgkmcnt(0)
	v_pk_mul_f32 v[166:167], v[150:151], v[130:131] op_sel_hi:[0,1]
	v_pk_mul_f32 v[168:169], v[150:151], v[128:129] op_sel_hi:[0,1]
	v_pk_mul_f32 v[2:3], v[166:167], v[2:3]
	v_pk_mul_f32 v[0:1], v[168:169], v[0:1]
	v_pk_mul_f32 v[166:167], v[156:157], v[130:131] op_sel_hi:[0,1]
	v_pk_mul_f32 v[168:169], v[156:157], v[128:129] op_sel_hi:[0,1]
	v_pk_mul_f32 v[6:7], v[166:167], v[6:7]
	v_pk_mul_f32 v[4:5], v[168:169], v[4:5]
	v_pk_mul_f32 v[166:167], v[148:149], v[130:131] op_sel_hi:[0,1]
	v_pk_mul_f32 v[168:169], v[148:149], v[128:129] op_sel_hi:[0,1]
	v_pk_mul_f32 v[14:15], v[166:167], v[14:15]
	v_pk_mul_f32 v[12:13], v[168:169], v[12:13]
	v_pk_mul_f32 v[166:167], v[158:159], v[130:131] op_sel_hi:[0,1]
	v_pk_mul_f32 v[168:169], v[158:159], v[128:129] op_sel_hi:[0,1]
	v_pk_mul_f32 v[10:11], v[166:167], v[10:11]
	v_pk_mul_f32 v[8:9], v[168:169], v[8:9]
	v_pk_mul_f32 v[166:167], v[134:135], v[130:131] op_sel_hi:[0,1]
	v_pk_mul_f32 v[168:169], v[134:135], v[128:129] op_sel_hi:[0,1]
	v_pk_mul_f32 v[22:23], v[166:167], v[22:23]
	v_pk_mul_f32 v[20:21], v[168:169], v[20:21]
	v_pk_mul_f32 v[166:167], v[160:161], v[130:131] op_sel_hi:[0,1]
	v_pk_mul_f32 v[168:169], v[160:161], v[128:129] op_sel_hi:[0,1]
	v_pk_mul_f32 v[18:19], v[166:167], v[18:19]
	v_pk_mul_f32 v[16:17], v[168:169], v[16:17]
	v_pk_mul_f32 v[166:167], v[132:133], v[130:131] op_sel_hi:[0,1]
	v_pk_mul_f32 v[168:169], v[132:133], v[128:129] op_sel_hi:[0,1]
	v_pk_mul_f32 v[130:131], v[130:131], v[152:153] op_sel_hi:[1,0]
	v_pk_mul_f32 v[128:129], v[128:129], v[152:153] op_sel_hi:[1,0]
	v_pk_mul_f32 v[26:27], v[166:167], v[26:27]
	v_pk_mul_f32 v[24:25], v[168:169], v[24:25]
	v_pk_mul_f32 v[30:31], v[130:131], v[30:31]
	v_pk_mul_f32 v[28:29], v[128:129], v[28:29]
	s_nop 0
	ds_read_b128 v[128:131], v230 offset:16
	v_cvt_f32_i32_e32 v57, v57
	v_cvt_f32_i32_e32 v56, v56
	v_cvt_f32_i32_e32 v59, v59
	v_cvt_f32_i32_e32 v58, v58
	v_cvt_f32_i32_e32 v53, v53
	v_cvt_f32_i32_e32 v52, v52
	v_cvt_f32_i32_e32 v55, v55
	v_cvt_f32_i32_e32 v54, v54
	v_cvt_f32_i32_e32 v49, v49
	v_cvt_f32_i32_e32 v48, v48
	v_cvt_f32_i32_e32 v51, v51
	v_cvt_f32_i32_e32 v50, v50
	v_cvt_f32_i32_e32 v45, v45
	v_cvt_f32_i32_e32 v44, v44
	v_cvt_f32_i32_e32 v47, v47
	v_cvt_f32_i32_e32 v46, v46
	v_cvt_f32_i32_e32 v41, v41
	v_cvt_f32_i32_e32 v40, v40
	v_cvt_f32_i32_e32 v43, v43
	v_cvt_f32_i32_e32 v42, v42
	v_cvt_f32_i32_e32 v37, v37
	v_cvt_f32_i32_e32 v36, v36
	v_cvt_f32_i32_e32 v39, v39
	v_cvt_f32_i32_e32 v38, v38
	v_cvt_f32_i32_e32 v33, v33
	v_cvt_f32_i32_e32 v32, v32
	v_cvt_f32_i32_e32 v35, v35
	v_cvt_f32_i32_e32 v34, v34
	v_cvt_f32_i32_e32 v61, v61
	v_cvt_f32_i32_e32 v60, v60
	v_cvt_f32_i32_e32 v63, v63
	v_cvt_f32_i32_e32 v62, v62
	s_waitcnt lgkmcnt(0)
	v_pk_mul_f32 v[166:167], v[150:151], v[130:131] op_sel_hi:[0,1]
	v_pk_mul_f32 v[168:169], v[150:151], v[128:129] op_sel_hi:[0,1]
	v_pk_mul_f32 v[58:59], v[166:167], v[58:59]
	v_pk_mul_f32 v[56:57], v[168:169], v[56:57]
	v_pk_mul_f32 v[166:167], v[156:157], v[130:131] op_sel_hi:[0,1]
	v_pk_mul_f32 v[168:169], v[156:157], v[128:129] op_sel_hi:[0,1]
	v_pk_mul_f32 v[54:55], v[166:167], v[54:55]
	v_pk_mul_f32 v[52:53], v[168:169], v[52:53]
	v_pk_mul_f32 v[166:167], v[148:149], v[130:131] op_sel_hi:[0,1]
	v_pk_mul_f32 v[168:169], v[148:149], v[128:129] op_sel_hi:[0,1]
	v_pk_mul_f32 v[50:51], v[166:167], v[50:51]
	v_pk_mul_f32 v[48:49], v[168:169], v[48:49]
	v_pk_mul_f32 v[166:167], v[158:159], v[130:131] op_sel_hi:[0,1]
	v_pk_mul_f32 v[168:169], v[158:159], v[128:129] op_sel_hi:[0,1]
	v_pk_mul_f32 v[46:47], v[166:167], v[46:47]
	v_pk_mul_f32 v[44:45], v[168:169], v[44:45]
	v_pk_mul_f32 v[166:167], v[134:135], v[130:131] op_sel_hi:[0,1]
	v_pk_mul_f32 v[168:169], v[134:135], v[128:129] op_sel_hi:[0,1]
	v_pk_mul_f32 v[42:43], v[166:167], v[42:43]
	v_pk_mul_f32 v[40:41], v[168:169], v[40:41]
	v_pk_mul_f32 v[166:167], v[160:161], v[130:131] op_sel_hi:[0,1]
	v_pk_mul_f32 v[168:169], v[160:161], v[128:129] op_sel_hi:[0,1]
	v_pk_mul_f32 v[38:39], v[166:167], v[38:39]
	v_pk_mul_f32 v[36:37], v[168:169], v[36:37]
	v_pk_mul_f32 v[166:167], v[132:133], v[130:131] op_sel_hi:[0,1]
	v_pk_mul_f32 v[168:169], v[132:133], v[128:129] op_sel_hi:[0,1]
	v_pk_mul_f32 v[130:131], v[152:153], v[130:131] op_sel_hi:[0,1]
	v_pk_mul_f32 v[128:129], v[152:153], v[128:129] op_sel_hi:[0,1]
	v_pk_mul_f32 v[34:35], v[166:167], v[34:35]
	v_pk_mul_f32 v[32:33], v[168:169], v[32:33]
	v_pk_mul_f32 v[62:63], v[130:131], v[62:63]
	v_pk_mul_f32 v[60:61], v[128:129], v[60:61]
	s_nop 0
	ds_read_b128 v[128:131], v230 offset:512
	v_cvt_f32_i32_e32 v89, v89
	v_cvt_f32_i32_e32 v88, v88
	v_cvt_f32_i32_e32 v91, v91
	v_cvt_f32_i32_e32 v90, v90
	v_cvt_f32_i32_e32 v85, v85
	v_cvt_f32_i32_e32 v84, v84
	v_cvt_f32_i32_e32 v87, v87
	v_cvt_f32_i32_e32 v86, v86
	v_cvt_f32_i32_e32 v81, v81
	v_cvt_f32_i32_e32 v80, v80
	v_cvt_f32_i32_e32 v83, v83
	v_cvt_f32_i32_e32 v82, v82
	v_cvt_f32_i32_e32 v77, v77
	v_cvt_f32_i32_e32 v76, v76
	v_cvt_f32_i32_e32 v79, v79
	v_cvt_f32_i32_e32 v78, v78
	v_cvt_f32_i32_e32 v73, v73
	v_cvt_f32_i32_e32 v72, v72
	v_cvt_f32_i32_e32 v75, v75
	v_cvt_f32_i32_e32 v74, v74
	v_cvt_f32_i32_e32 v69, v69
	v_cvt_f32_i32_e32 v68, v68
	v_cvt_f32_i32_e32 v71, v71
	v_cvt_f32_i32_e32 v70, v70
	v_cvt_f32_i32_e32 v65, v65
	v_cvt_f32_i32_e32 v64, v64
	v_cvt_f32_i32_e32 v67, v67
	v_cvt_f32_i32_e32 v66, v66
	v_cvt_f32_i32_e32 v93, v93
	v_cvt_f32_i32_e32 v92, v92
	v_cvt_f32_i32_e32 v95, v95
	v_cvt_f32_i32_e32 v94, v94
	s_waitcnt lgkmcnt(0)
	v_pk_mul_f32 v[166:167], v[150:151], v[130:131] op_sel_hi:[0,1]
	v_pk_mul_f32 v[168:169], v[150:151], v[128:129] op_sel_hi:[0,1]
	v_pk_mul_f32 v[90:91], v[166:167], v[90:91]
	v_pk_mul_f32 v[88:89], v[168:169], v[88:89]
	v_pk_mul_f32 v[166:167], v[156:157], v[130:131] op_sel_hi:[0,1]
	v_pk_mul_f32 v[168:169], v[156:157], v[128:129] op_sel_hi:[0,1]
	v_pk_mul_f32 v[86:87], v[166:167], v[86:87]
	v_pk_mul_f32 v[84:85], v[168:169], v[84:85]
	v_pk_mul_f32 v[166:167], v[148:149], v[130:131] op_sel_hi:[0,1]
	v_pk_mul_f32 v[168:169], v[148:149], v[128:129] op_sel_hi:[0,1]
	v_pk_mul_f32 v[82:83], v[166:167], v[82:83]
	v_pk_mul_f32 v[80:81], v[168:169], v[80:81]
	v_pk_mul_f32 v[166:167], v[158:159], v[130:131] op_sel_hi:[0,1]
	v_pk_mul_f32 v[168:169], v[158:159], v[128:129] op_sel_hi:[0,1]
	v_pk_mul_f32 v[78:79], v[166:167], v[78:79]
	v_pk_mul_f32 v[76:77], v[168:169], v[76:77]
	v_pk_mul_f32 v[166:167], v[134:135], v[130:131] op_sel_hi:[0,1]
	v_pk_mul_f32 v[168:169], v[134:135], v[128:129] op_sel_hi:[0,1]
	v_pk_mul_f32 v[74:75], v[166:167], v[74:75]
	v_pk_mul_f32 v[72:73], v[168:169], v[72:73]
	v_pk_mul_f32 v[166:167], v[160:161], v[130:131] op_sel_hi:[0,1]
	v_pk_mul_f32 v[168:169], v[160:161], v[128:129] op_sel_hi:[0,1]
	v_pk_mul_f32 v[70:71], v[166:167], v[70:71]
	v_pk_mul_f32 v[68:69], v[168:169], v[68:69]
	v_pk_mul_f32 v[166:167], v[132:133], v[130:131] op_sel_hi:[0,1]
	v_pk_mul_f32 v[168:169], v[132:133], v[128:129] op_sel_hi:[0,1]
	v_pk_mul_f32 v[130:131], v[152:153], v[130:131] op_sel_hi:[0,1]
	v_pk_mul_f32 v[128:129], v[152:153], v[128:129] op_sel_hi:[0,1]
	v_pk_mul_f32 v[66:67], v[166:167], v[66:67]
	v_pk_mul_f32 v[64:65], v[168:169], v[64:65]
	v_pk_mul_f32 v[94:95], v[130:131], v[94:95]
	v_pk_mul_f32 v[92:93], v[128:129], v[92:93]
	s_nop 0
	ds_read_b128 v[128:131], v230 offset:528
	v_cvt_f32_i32_e32 v121, v121
	v_cvt_f32_i32_e32 v120, v120
	v_cvt_f32_i32_e32 v119, v119
	v_cvt_f32_i32_e32 v118, v118
	v_cvt_f32_i32_e32 v113, v113
	v_cvt_f32_i32_e32 v112, v112
	v_cvt_f32_i32_e32 v111, v111
	v_cvt_f32_i32_e32 v110, v110
	v_cvt_f32_i32_e32 v105, v105
	v_cvt_f32_i32_e32 v104, v104
	v_cvt_f32_i32_e32 v123, v123
	v_cvt_f32_i32_e32 v122, v122
	v_cvt_f32_i32_e32 v115, v115
	v_cvt_f32_i32_e32 v114, v114
	v_cvt_f32_i32_e32 v107, v107
	v_cvt_f32_i32_e32 v106, v106
	v_cvt_f32_i32_e32 v103, v103
	v_cvt_f32_i32_e32 v102, v102
	v_cvt_f32_i32_e32 v117, v117
	v_cvt_f32_i32_e32 v116, v116
	v_cvt_f32_i32_e32 v109, v109
	v_cvt_f32_i32_e32 v108, v108
	v_cvt_f32_i32_e32 v101, v101
	v_cvt_f32_i32_e32 v100, v100
	v_cvt_f32_i32_e32 v97, v97
	v_cvt_f32_i32_e32 v96, v96
	v_cvt_f32_i32_e32 v99, v99
	v_cvt_f32_i32_e32 v98, v98
	v_cvt_f32_i32_e32 v125, v125
	v_cvt_f32_i32_e32 v124, v124
	v_cvt_f32_i32_e32 v127, v127
	v_cvt_f32_i32_e32 v126, v126
	s_waitcnt lgkmcnt(0)
	v_pk_mul_f32 v[154:155], v[150:151], v[130:131] op_sel_hi:[0,1]
	v_pk_mul_f32 v[150:151], v[150:151], v[128:129] op_sel_hi:[0,1]
	v_pk_mul_f32 v[120:121], v[150:151], v[120:121]
	v_pk_mul_f32 v[150:151], v[156:157], v[130:131] op_sel_hi:[0,1]
	v_pk_mul_f32 v[118:119], v[150:151], v[118:119]
	v_pk_mul_f32 v[150:151], v[148:149], v[130:131] op_sel_hi:[0,1]
	v_pk_mul_f32 v[148:149], v[148:149], v[128:129] op_sel_hi:[0,1]
	v_pk_mul_f32 v[112:113], v[148:149], v[112:113]
	v_pk_mul_f32 v[148:149], v[158:159], v[130:131] op_sel_hi:[0,1]
	v_pk_mul_f32 v[110:111], v[148:149], v[110:111]
	v_pk_mul_f32 v[148:149], v[134:135], v[130:131] op_sel_hi:[0,1]
	v_pk_mul_f32 v[134:135], v[134:135], v[128:129] op_sel_hi:[0,1]
	v_pk_mul_f32 v[104:105], v[134:135], v[104:105]
	v_pk_mul_f32 v[134:135], v[160:161], v[130:131] op_sel_hi:[0,1]
	v_pk_mul_f32 v[122:123], v[154:155], v[122:123]
	v_pk_mul_f32 v[154:155], v[156:157], v[128:129] op_sel_hi:[0,1]
	v_pk_mul_f32 v[114:115], v[150:151], v[114:115]
	v_pk_mul_f32 v[150:151], v[158:159], v[128:129] op_sel_hi:[0,1]
	v_pk_mul_f32 v[106:107], v[148:149], v[106:107]
	v_pk_mul_f32 v[148:149], v[160:161], v[128:129] op_sel_hi:[0,1]
	v_pk_mul_f32 v[102:103], v[134:135], v[102:103]
	v_pk_mul_f32 v[134:135], v[132:133], v[130:131] op_sel_hi:[0,1]
	v_pk_mul_f32 v[132:133], v[132:133], v[128:129] op_sel_hi:[0,1]
	v_pk_mul_f32 v[130:131], v[152:153], v[130:131] op_sel_hi:[0,1]
	v_pk_mul_f32 v[128:129], v[152:153], v[128:129] op_sel_hi:[0,1]
	v_pk_mul_f32 v[116:117], v[154:155], v[116:117]
	v_pk_mul_f32 v[108:109], v[150:151], v[108:109]
	v_pk_mul_f32 v[100:101], v[148:149], v[100:101]
	v_pk_mul_f32 v[98:99], v[134:135], v[98:99]
	v_pk_mul_f32 v[96:97], v[132:133], v[96:97]
	v_pk_mul_f32 v[126:127], v[130:131], v[126:127]
	v_pk_mul_f32 v[124:125], v[128:129], v[124:125]
	s_nop 0
	s_cmp_gt_i32 s36, 1
	s_cbranch_scc1 .LBB0_234
	v_and_b32_e32 v129, 0x7fffffff, v1
	v_and_b32_e32 v128, 0x7fffffff, v0
	v_pk_fma_f32 v[128:129], v[128:129], s[62:63], 1.0 op_sel_hi:[1,0,0]
	s_mov_b32 s14, 0xbf3a00e3
	v_rcp_f32_e32 v130, v128
	v_rcp_f32_e32 v131, v129
	v_mov_b64_e32 v[128:129], s[14:15]
	v_pk_mul_f32 v[134:135], v[0:1], v[0:1]
	v_cmp_gt_f32_e32 vcc, 0, v0
	v_pk_fma_f32 v[132:133], v[130:131], s[92:93], v[128:129] op_sel_hi:[1,0,0]
	v_pk_mul_f32 v[134:135], v[134:135], s[0:1] op_sel_hi:[1,0]
	v_pk_fma_f32 v[132:133], v[130:131], v[132:133], s[94:95] op_sel_hi:[1,1,0]
	v_exp_f32_e32 v134, v134
	v_exp_f32_e32 v135, v135
	v_pk_fma_f32 v[132:133], v[130:131], v[132:133], s[96:97] op_sel_hi:[1,1,0]
	s_nop 0
	v_pk_fma_f32 v[132:133], v[130:131], v[132:133], s[74:75] op_sel_hi:[1,1,0]
	s_nop 0
	v_pk_mul_f32 v[130:131], v[130:131], v[132:133]
	v_pk_mul_f32 v[132:133], v[2:3], v[2:3]
	v_pk_mul_f32 v[130:131], v[134:135], v[130:131]
	v_pk_mul_f32 v[132:133], v[132:133], s[0:1] op_sel_hi:[1,0]
	v_pk_mul_f32 v[134:135], v[0:1], v[130:131]
	v_pk_fma_f32 v[130:131], v[0:1], v[130:131], v[0:1] neg_lo:[1,0,0] neg_hi:[1,0,0]
	v_exp_f32_e32 v132, v132
	v_cndmask_b32_e32 v0, v130, v134, vcc
	v_cmp_gt_f32_e32 vcc, 0, v1
	v_and_b32_e32 v130, 0x7fffffff, v2
	v_exp_f32_e32 v133, v133
	v_cndmask_b32_e32 v1, v131, v135, vcc
	v_and_b32_e32 v131, 0x7fffffff, v3
	v_pk_fma_f32 v[130:131], v[130:131], s[62:63], 1.0 op_sel_hi:[1,0,0]
	v_cmp_gt_f32_e32 vcc, 0, v2
	v_rcp_f32_e32 v130, v130
	v_rcp_f32_e32 v131, v131
	s_nop 0
	v_pk_fma_f32 v[134:135], v[130:131], s[92:93], v[128:129] op_sel_hi:[1,0,0]
	s_nop 0
	v_pk_fma_f32 v[134:135], v[130:131], v[134:135], s[94:95] op_sel_hi:[1,1,0]
	s_nop 0
	v_pk_fma_f32 v[134:135], v[130:131], v[134:135], s[96:97] op_sel_hi:[1,1,0]
	s_nop 0
	v_pk_fma_f32 v[134:135], v[130:131], v[134:135], s[74:75] op_sel_hi:[1,1,0]
	s_nop 0
	v_pk_mul_f32 v[130:131], v[130:131], v[134:135]
	v_pk_mul_f32 v[134:135], v[56:57], v[56:57]
	v_pk_mul_f32 v[130:131], v[132:133], v[130:131]
	v_pk_mul_f32 v[134:135], v[134:135], s[0:1] op_sel_hi:[1,0]
	v_pk_mul_f32 v[132:133], v[2:3], v[130:131]
	v_pk_fma_f32 v[130:131], v[2:3], v[130:131], v[2:3] neg_lo:[1,0,0] neg_hi:[1,0,0]
	v_exp_f32_e32 v134, v134
	v_cndmask_b32_e32 v2, v130, v132, vcc
	v_cmp_gt_f32_e32 vcc, 0, v3
	v_and_b32_e32 v130, 0x7fffffff, v56
	v_exp_f32_e32 v135, v135
	v_cndmask_b32_e32 v3, v131, v133, vcc
	v_and_b32_e32 v131, 0x7fffffff, v57
	v_pk_fma_f32 v[130:131], v[130:131], s[62:63], 1.0 op_sel_hi:[1,0,0]
	v_cmp_gt_f32_e32 vcc, 0, v56
	v_rcp_f32_e32 v130, v130
	v_rcp_f32_e32 v131, v131
	s_nop 0
	v_pk_fma_f32 v[132:133], v[130:131], s[92:93], v[128:129] op_sel_hi:[1,0,0]
	s_nop 0
	v_pk_fma_f32 v[132:133], v[130:131], v[132:133], s[94:95] op_sel_hi:[1,1,0]
	s_nop 0
	v_pk_fma_f32 v[132:133], v[130:131], v[132:133], s[96:97] op_sel_hi:[1,1,0]
	s_nop 0
	v_pk_fma_f32 v[132:133], v[130:131], v[132:133], s[74:75] op_sel_hi:[1,1,0]
	s_nop 0
	v_pk_mul_f32 v[130:131], v[130:131], v[132:133]
	v_pk_mul_f32 v[132:133], v[58:59], v[58:59]
	v_pk_mul_f32 v[130:131], v[134:135], v[130:131]
	v_pk_mul_f32 v[132:133], v[132:133], s[0:1] op_sel_hi:[1,0]
	v_pk_mul_f32 v[134:135], v[56:57], v[130:131]
	v_pk_fma_f32 v[130:131], v[56:57], v[130:131], v[56:57] neg_lo:[1,0,0] neg_hi:[1,0,0]
	v_exp_f32_e32 v132, v132
	v_cndmask_b32_e32 v56, v130, v134, vcc
	v_cmp_gt_f32_e32 vcc, 0, v57
	v_and_b32_e32 v130, 0x7fffffff, v58
	v_exp_f32_e32 v133, v133
	v_cndmask_b32_e32 v57, v131, v135, vcc
	v_and_b32_e32 v131, 0x7fffffff, v59
	v_pk_fma_f32 v[130:131], v[130:131], s[62:63], 1.0 op_sel_hi:[1,0,0]
	v_cmp_gt_f32_e32 vcc, 0, v58
	v_rcp_f32_e32 v130, v130
	v_rcp_f32_e32 v131, v131
	s_nop 0
	v_pk_fma_f32 v[134:135], v[130:131], s[92:93], v[128:129] op_sel_hi:[1,0,0]
	s_nop 0
	v_pk_fma_f32 v[134:135], v[130:131], v[134:135], s[94:95] op_sel_hi:[1,1,0]
	s_nop 0
	v_pk_fma_f32 v[134:135], v[130:131], v[134:135], s[96:97] op_sel_hi:[1,1,0]
	s_nop 0
	v_pk_fma_f32 v[134:135], v[130:131], v[134:135], s[74:75] op_sel_hi:[1,1,0]
	s_nop 0
	v_pk_mul_f32 v[130:131], v[130:131], v[134:135]
	v_pk_mul_f32 v[134:135], v[4:5], v[4:5]
	v_pk_mul_f32 v[130:131], v[132:133], v[130:131]
	v_pk_mul_f32 v[134:135], v[134:135], s[0:1] op_sel_hi:[1,0]
	v_pk_mul_f32 v[132:133], v[58:59], v[130:131]
	v_pk_fma_f32 v[130:131], v[58:59], v[130:131], v[58:59] neg_lo:[1,0,0] neg_hi:[1,0,0]
	v_exp_f32_e32 v134, v134
	v_cndmask_b32_e32 v58, v130, v132, vcc
	v_cmp_gt_f32_e32 vcc, 0, v59
	v_and_b32_e32 v130, 0x7fffffff, v4
	v_exp_f32_e32 v135, v135
	v_cndmask_b32_e32 v59, v131, v133, vcc
	v_and_b32_e32 v131, 0x7fffffff, v5
	v_pk_fma_f32 v[130:131], v[130:131], s[62:63], 1.0 op_sel_hi:[1,0,0]
	v_cmp_gt_f32_e32 vcc, 0, v4
	v_rcp_f32_e32 v130, v130
	v_rcp_f32_e32 v131, v131
	s_nop 0
	v_pk_fma_f32 v[132:133], v[130:131], s[92:93], v[128:129] op_sel_hi:[1,0,0]
	s_nop 0
	v_pk_fma_f32 v[132:133], v[130:131], v[132:133], s[94:95] op_sel_hi:[1,1,0]
	s_nop 0
	v_pk_fma_f32 v[132:133], v[130:131], v[132:133], s[96:97] op_sel_hi:[1,1,0]
	s_nop 0
	v_pk_fma_f32 v[132:133], v[130:131], v[132:133], s[74:75] op_sel_hi:[1,1,0]
	s_nop 0
	v_pk_mul_f32 v[130:131], v[130:131], v[132:133]
	v_pk_mul_f32 v[132:133], v[6:7], v[6:7]
	v_pk_mul_f32 v[130:131], v[134:135], v[130:131]
	v_pk_mul_f32 v[132:133], v[132:133], s[0:1] op_sel_hi:[1,0]
	v_pk_mul_f32 v[134:135], v[4:5], v[130:131]
	v_pk_fma_f32 v[130:131], v[4:5], v[130:131], v[4:5] neg_lo:[1,0,0] neg_hi:[1,0,0]
	v_exp_f32_e32 v132, v132
	v_cndmask_b32_e32 v4, v130, v134, vcc
	v_cmp_gt_f32_e32 vcc, 0, v5
	v_and_b32_e32 v130, 0x7fffffff, v6
	v_exp_f32_e32 v133, v133
	v_cndmask_b32_e32 v5, v131, v135, vcc
	v_and_b32_e32 v131, 0x7fffffff, v7
	v_pk_fma_f32 v[130:131], v[130:131], s[62:63], 1.0 op_sel_hi:[1,0,0]
	v_cmp_gt_f32_e32 vcc, 0, v6
	v_rcp_f32_e32 v130, v130
	v_rcp_f32_e32 v131, v131
	s_nop 0
	v_pk_fma_f32 v[134:135], v[130:131], s[92:93], v[128:129] op_sel_hi:[1,0,0]
	s_nop 0
	v_pk_fma_f32 v[134:135], v[130:131], v[134:135], s[94:95] op_sel_hi:[1,1,0]
	s_nop 0
	v_pk_fma_f32 v[134:135], v[130:131], v[134:135], s[96:97] op_sel_hi:[1,1,0]
	s_nop 0
	v_pk_fma_f32 v[134:135], v[130:131], v[134:135], s[74:75] op_sel_hi:[1,1,0]
	s_nop 0
	v_pk_mul_f32 v[130:131], v[130:131], v[134:135]
	v_pk_mul_f32 v[134:135], v[52:53], v[52:53]
	v_pk_mul_f32 v[130:131], v[132:133], v[130:131]
	v_pk_mul_f32 v[134:135], v[134:135], s[0:1] op_sel_hi:[1,0]
	v_pk_mul_f32 v[132:133], v[6:7], v[130:131]
	v_pk_fma_f32 v[130:131], v[6:7], v[130:131], v[6:7] neg_lo:[1,0,0] neg_hi:[1,0,0]
	v_exp_f32_e32 v134, v134
	v_cndmask_b32_e32 v6, v130, v132, vcc
	v_cmp_gt_f32_e32 vcc, 0, v7
	v_and_b32_e32 v130, 0x7fffffff, v52
	v_exp_f32_e32 v135, v135
	v_cndmask_b32_e32 v7, v131, v133, vcc
	v_and_b32_e32 v131, 0x7fffffff, v53
	v_pk_fma_f32 v[130:131], v[130:131], s[62:63], 1.0 op_sel_hi:[1,0,0]
	v_cmp_gt_f32_e32 vcc, 0, v52
	v_rcp_f32_e32 v130, v130
	v_rcp_f32_e32 v131, v131
	s_nop 0
	v_pk_fma_f32 v[132:133], v[130:131], s[92:93], v[128:129] op_sel_hi:[1,0,0]
	s_nop 0
	v_pk_fma_f32 v[132:133], v[130:131], v[132:133], s[94:95] op_sel_hi:[1,1,0]
	s_nop 0
	v_pk_fma_f32 v[132:133], v[130:131], v[132:133], s[96:97] op_sel_hi:[1,1,0]
	s_nop 0
	v_pk_fma_f32 v[132:133], v[130:131], v[132:133], s[74:75] op_sel_hi:[1,1,0]
	s_nop 0
	v_pk_mul_f32 v[130:131], v[130:131], v[132:133]
	v_pk_mul_f32 v[132:133], v[54:55], v[54:55]
	v_pk_mul_f32 v[130:131], v[134:135], v[130:131]
	v_pk_mul_f32 v[132:133], v[132:133], s[0:1] op_sel_hi:[1,0]
	v_pk_mul_f32 v[134:135], v[52:53], v[130:131]
	v_pk_fma_f32 v[130:131], v[52:53], v[130:131], v[52:53] neg_lo:[1,0,0] neg_hi:[1,0,0]
	v_exp_f32_e32 v132, v132
	v_cndmask_b32_e32 v52, v130, v134, vcc
	v_cmp_gt_f32_e32 vcc, 0, v53
	v_and_b32_e32 v130, 0x7fffffff, v54
	v_exp_f32_e32 v133, v133
	v_cndmask_b32_e32 v53, v131, v135, vcc
	v_and_b32_e32 v131, 0x7fffffff, v55
	v_pk_fma_f32 v[130:131], v[130:131], s[62:63], 1.0 op_sel_hi:[1,0,0]
	v_cmp_gt_f32_e32 vcc, 0, v54
	v_rcp_f32_e32 v130, v130
	v_rcp_f32_e32 v131, v131
	s_nop 0
	v_pk_fma_f32 v[134:135], v[130:131], s[92:93], v[128:129] op_sel_hi:[1,0,0]
	s_nop 0
	v_pk_fma_f32 v[134:135], v[130:131], v[134:135], s[94:95] op_sel_hi:[1,1,0]
	s_nop 0
	v_pk_fma_f32 v[134:135], v[130:131], v[134:135], s[96:97] op_sel_hi:[1,1,0]
	s_nop 0
	v_pk_fma_f32 v[134:135], v[130:131], v[134:135], s[74:75] op_sel_hi:[1,1,0]
	s_nop 0
	v_pk_mul_f32 v[130:131], v[130:131], v[134:135]
	v_pk_mul_f32 v[134:135], v[12:13], v[12:13]
	v_pk_mul_f32 v[130:131], v[132:133], v[130:131]
	v_pk_mul_f32 v[134:135], v[134:135], s[0:1] op_sel_hi:[1,0]
	v_pk_mul_f32 v[132:133], v[54:55], v[130:131]
	v_pk_fma_f32 v[130:131], v[54:55], v[130:131], v[54:55] neg_lo:[1,0,0] neg_hi:[1,0,0]
	v_exp_f32_e32 v134, v134
	v_cndmask_b32_e32 v54, v130, v132, vcc
	v_cmp_gt_f32_e32 vcc, 0, v55
	v_and_b32_e32 v130, 0x7fffffff, v12
	v_exp_f32_e32 v135, v135
	v_cndmask_b32_e32 v55, v131, v133, vcc
	v_and_b32_e32 v131, 0x7fffffff, v13
	v_pk_fma_f32 v[130:131], v[130:131], s[62:63], 1.0 op_sel_hi:[1,0,0]
	v_cmp_gt_f32_e32 vcc, 0, v12
	v_rcp_f32_e32 v130, v130
	v_rcp_f32_e32 v131, v131
	s_nop 0
	v_pk_fma_f32 v[132:133], v[130:131], s[92:93], v[128:129] op_sel_hi:[1,0,0]
	s_nop 0
	v_pk_fma_f32 v[132:133], v[130:131], v[132:133], s[94:95] op_sel_hi:[1,1,0]
	s_nop 0
	v_pk_fma_f32 v[132:133], v[130:131], v[132:133], s[96:97] op_sel_hi:[1,1,0]
	s_nop 0
	v_pk_fma_f32 v[132:133], v[130:131], v[132:133], s[74:75] op_sel_hi:[1,1,0]
	s_nop 0
	v_pk_mul_f32 v[130:131], v[130:131], v[132:133]
	v_pk_mul_f32 v[132:133], v[14:15], v[14:15]
	v_pk_mul_f32 v[130:131], v[134:135], v[130:131]
	v_pk_mul_f32 v[132:133], v[132:133], s[0:1] op_sel_hi:[1,0]
	v_pk_mul_f32 v[134:135], v[12:13], v[130:131]
	v_pk_fma_f32 v[130:131], v[12:13], v[130:131], v[12:13] neg_lo:[1,0,0] neg_hi:[1,0,0]
	v_exp_f32_e32 v132, v132
	v_cndmask_b32_e32 v12, v130, v134, vcc
	v_cmp_gt_f32_e32 vcc, 0, v13
	v_and_b32_e32 v130, 0x7fffffff, v14
	v_exp_f32_e32 v133, v133
	v_cndmask_b32_e32 v13, v131, v135, vcc
	v_and_b32_e32 v131, 0x7fffffff, v15
	v_pk_fma_f32 v[130:131], v[130:131], s[62:63], 1.0 op_sel_hi:[1,0,0]
	v_cmp_gt_f32_e32 vcc, 0, v14
	v_rcp_f32_e32 v130, v130
	v_rcp_f32_e32 v131, v131
	s_nop 0
	v_pk_fma_f32 v[134:135], v[130:131], s[92:93], v[128:129] op_sel_hi:[1,0,0]
	s_nop 0
	v_pk_fma_f32 v[134:135], v[130:131], v[134:135], s[94:95] op_sel_hi:[1,1,0]
	s_nop 0
	v_pk_fma_f32 v[134:135], v[130:131], v[134:135], s[96:97] op_sel_hi:[1,1,0]
	s_nop 0
	v_pk_fma_f32 v[134:135], v[130:131], v[134:135], s[74:75] op_sel_hi:[1,1,0]
	s_nop 0
	v_pk_mul_f32 v[130:131], v[130:131], v[134:135]
	v_pk_mul_f32 v[134:135], v[48:49], v[48:49]
	v_pk_mul_f32 v[130:131], v[132:133], v[130:131]
	v_pk_mul_f32 v[134:135], v[134:135], s[0:1] op_sel_hi:[1,0]
	v_pk_mul_f32 v[132:133], v[14:15], v[130:131]
	v_pk_fma_f32 v[130:131], v[14:15], v[130:131], v[14:15] neg_lo:[1,0,0] neg_hi:[1,0,0]
	v_exp_f32_e32 v134, v134
	v_cndmask_b32_e32 v14, v130, v132, vcc
	v_cmp_gt_f32_e32 vcc, 0, v15
	v_and_b32_e32 v130, 0x7fffffff, v48
	v_exp_f32_e32 v135, v135
	v_cndmask_b32_e32 v15, v131, v133, vcc
	v_and_b32_e32 v131, 0x7fffffff, v49
	v_pk_fma_f32 v[130:131], v[130:131], s[62:63], 1.0 op_sel_hi:[1,0,0]
	v_cmp_gt_f32_e32 vcc, 0, v48
	v_rcp_f32_e32 v130, v130
	v_rcp_f32_e32 v131, v131
	s_nop 0
	v_pk_fma_f32 v[132:133], v[130:131], s[92:93], v[128:129] op_sel_hi:[1,0,0]
	s_nop 0
	v_pk_fma_f32 v[132:133], v[130:131], v[132:133], s[94:95] op_sel_hi:[1,1,0]
	s_nop 0
	v_pk_fma_f32 v[132:133], v[130:131], v[132:133], s[96:97] op_sel_hi:[1,1,0]
	s_nop 0
	v_pk_fma_f32 v[132:133], v[130:131], v[132:133], s[74:75] op_sel_hi:[1,1,0]
	s_nop 0
	v_pk_mul_f32 v[130:131], v[130:131], v[132:133]
	v_pk_mul_f32 v[132:133], v[50:51], v[50:51]
	v_pk_mul_f32 v[130:131], v[134:135], v[130:131]
	v_pk_mul_f32 v[132:133], v[132:133], s[0:1] op_sel_hi:[1,0]
	v_pk_mul_f32 v[134:135], v[48:49], v[130:131]
	v_pk_fma_f32 v[130:131], v[48:49], v[130:131], v[48:49] neg_lo:[1,0,0] neg_hi:[1,0,0]
	v_exp_f32_e32 v132, v132
	v_cndmask_b32_e32 v48, v130, v134, vcc
	v_cmp_gt_f32_e32 vcc, 0, v49
	v_and_b32_e32 v130, 0x7fffffff, v50
	v_exp_f32_e32 v133, v133
	v_cndmask_b32_e32 v49, v131, v135, vcc
	v_and_b32_e32 v131, 0x7fffffff, v51
	v_pk_fma_f32 v[130:131], v[130:131], s[62:63], 1.0 op_sel_hi:[1,0,0]
	v_cmp_gt_f32_e32 vcc, 0, v50
	v_rcp_f32_e32 v130, v130
	v_rcp_f32_e32 v131, v131
	s_nop 0
	v_pk_fma_f32 v[134:135], v[130:131], s[92:93], v[128:129] op_sel_hi:[1,0,0]
	s_nop 0
	v_pk_fma_f32 v[134:135], v[130:131], v[134:135], s[94:95] op_sel_hi:[1,1,0]
	s_nop 0
	v_pk_fma_f32 v[134:135], v[130:131], v[134:135], s[96:97] op_sel_hi:[1,1,0]
	s_nop 0
	v_pk_fma_f32 v[134:135], v[130:131], v[134:135], s[74:75] op_sel_hi:[1,1,0]
	s_nop 0
	v_pk_mul_f32 v[130:131], v[130:131], v[134:135]
	v_pk_mul_f32 v[134:135], v[8:9], v[8:9]
	v_pk_mul_f32 v[130:131], v[132:133], v[130:131]
	v_pk_mul_f32 v[134:135], v[134:135], s[0:1] op_sel_hi:[1,0]
	v_pk_mul_f32 v[132:133], v[50:51], v[130:131]
	v_pk_fma_f32 v[130:131], v[50:51], v[130:131], v[50:51] neg_lo:[1,0,0] neg_hi:[1,0,0]
	v_exp_f32_e32 v134, v134
	v_cndmask_b32_e32 v50, v130, v132, vcc
	v_cmp_gt_f32_e32 vcc, 0, v51
	v_and_b32_e32 v130, 0x7fffffff, v8
	v_exp_f32_e32 v135, v135
	v_cndmask_b32_e32 v51, v131, v133, vcc
	v_and_b32_e32 v131, 0x7fffffff, v9
	v_pk_fma_f32 v[130:131], v[130:131], s[62:63], 1.0 op_sel_hi:[1,0,0]
	v_cmp_gt_f32_e32 vcc, 0, v8
	v_rcp_f32_e32 v130, v130
	v_rcp_f32_e32 v131, v131
	s_nop 0
	v_pk_fma_f32 v[132:133], v[130:131], s[92:93], v[128:129] op_sel_hi:[1,0,0]
	s_nop 0
	v_pk_fma_f32 v[132:133], v[130:131], v[132:133], s[94:95] op_sel_hi:[1,1,0]
	s_nop 0
	v_pk_fma_f32 v[132:133], v[130:131], v[132:133], s[96:97] op_sel_hi:[1,1,0]
	s_nop 0
	v_pk_fma_f32 v[132:133], v[130:131], v[132:133], s[74:75] op_sel_hi:[1,1,0]
	s_nop 0
	v_pk_mul_f32 v[130:131], v[130:131], v[132:133]
	v_pk_mul_f32 v[132:133], v[10:11], v[10:11]
	v_pk_mul_f32 v[130:131], v[134:135], v[130:131]
	v_pk_mul_f32 v[132:133], v[132:133], s[0:1] op_sel_hi:[1,0]
	v_pk_mul_f32 v[134:135], v[8:9], v[130:131]
	v_pk_fma_f32 v[130:131], v[8:9], v[130:131], v[8:9] neg_lo:[1,0,0] neg_hi:[1,0,0]
	v_exp_f32_e32 v132, v132
	v_cndmask_b32_e32 v8, v130, v134, vcc
	v_cmp_gt_f32_e32 vcc, 0, v9
	v_and_b32_e32 v130, 0x7fffffff, v10
	v_exp_f32_e32 v133, v133
	v_cndmask_b32_e32 v9, v131, v135, vcc
	v_and_b32_e32 v131, 0x7fffffff, v11
	v_pk_fma_f32 v[130:131], v[130:131], s[62:63], 1.0 op_sel_hi:[1,0,0]
	v_cmp_gt_f32_e32 vcc, 0, v10
	v_rcp_f32_e32 v130, v130
	v_rcp_f32_e32 v131, v131
	s_nop 0
	v_pk_fma_f32 v[134:135], v[130:131], s[92:93], v[128:129] op_sel_hi:[1,0,0]
	s_nop 0
	v_pk_fma_f32 v[134:135], v[130:131], v[134:135], s[94:95] op_sel_hi:[1,1,0]
	s_nop 0
	v_pk_fma_f32 v[134:135], v[130:131], v[134:135], s[96:97] op_sel_hi:[1,1,0]
	s_nop 0
	v_pk_fma_f32 v[134:135], v[130:131], v[134:135], s[74:75] op_sel_hi:[1,1,0]
	s_nop 0
	v_pk_mul_f32 v[130:131], v[130:131], v[134:135]
	v_pk_mul_f32 v[134:135], v[44:45], v[44:45]
	v_pk_mul_f32 v[130:131], v[132:133], v[130:131]
	v_pk_mul_f32 v[134:135], v[134:135], s[0:1] op_sel_hi:[1,0]
	v_pk_mul_f32 v[132:133], v[10:11], v[130:131]
	v_pk_fma_f32 v[130:131], v[10:11], v[130:131], v[10:11] neg_lo:[1,0,0] neg_hi:[1,0,0]
	v_exp_f32_e32 v134, v134
	v_cndmask_b32_e32 v10, v130, v132, vcc
	v_cmp_gt_f32_e32 vcc, 0, v11
	v_and_b32_e32 v130, 0x7fffffff, v44
	v_exp_f32_e32 v135, v135
	v_cndmask_b32_e32 v11, v131, v133, vcc
	v_and_b32_e32 v131, 0x7fffffff, v45
	v_pk_fma_f32 v[130:131], v[130:131], s[62:63], 1.0 op_sel_hi:[1,0,0]
	v_cmp_gt_f32_e32 vcc, 0, v44
	v_rcp_f32_e32 v130, v130
	v_rcp_f32_e32 v131, v131
	s_nop 0
	v_pk_fma_f32 v[132:133], v[130:131], s[92:93], v[128:129] op_sel_hi:[1,0,0]
	s_nop 0
	v_pk_fma_f32 v[132:133], v[130:131], v[132:133], s[94:95] op_sel_hi:[1,1,0]
	s_nop 0
	v_pk_fma_f32 v[132:133], v[130:131], v[132:133], s[96:97] op_sel_hi:[1,1,0]
	s_nop 0
	v_pk_fma_f32 v[132:133], v[130:131], v[132:133], s[74:75] op_sel_hi:[1,1,0]
	s_nop 0
	v_pk_mul_f32 v[130:131], v[130:131], v[132:133]
	v_pk_mul_f32 v[132:133], v[46:47], v[46:47]
	v_pk_mul_f32 v[130:131], v[134:135], v[130:131]
	v_pk_mul_f32 v[132:133], v[132:133], s[0:1] op_sel_hi:[1,0]
	v_pk_mul_f32 v[134:135], v[44:45], v[130:131]
	v_pk_fma_f32 v[130:131], v[44:45], v[130:131], v[44:45] neg_lo:[1,0,0] neg_hi:[1,0,0]
	v_exp_f32_e32 v132, v132
	v_cndmask_b32_e32 v44, v130, v134, vcc
	v_cmp_gt_f32_e32 vcc, 0, v45
	v_and_b32_e32 v130, 0x7fffffff, v46
	v_exp_f32_e32 v133, v133
	v_cndmask_b32_e32 v45, v131, v135, vcc
	v_and_b32_e32 v131, 0x7fffffff, v47
	v_pk_fma_f32 v[130:131], v[130:131], s[62:63], 1.0 op_sel_hi:[1,0,0]
	v_cmp_gt_f32_e32 vcc, 0, v46
	v_rcp_f32_e32 v130, v130
	v_rcp_f32_e32 v131, v131
	s_nop 0
	v_pk_fma_f32 v[134:135], v[130:131], s[92:93], v[128:129] op_sel_hi:[1,0,0]
	s_nop 0
	v_pk_fma_f32 v[134:135], v[130:131], v[134:135], s[94:95] op_sel_hi:[1,1,0]
	s_nop 0
	v_pk_fma_f32 v[134:135], v[130:131], v[134:135], s[96:97] op_sel_hi:[1,1,0]
	s_nop 0
	v_pk_fma_f32 v[134:135], v[130:131], v[134:135], s[74:75] op_sel_hi:[1,1,0]
	s_nop 0
	v_pk_mul_f32 v[130:131], v[130:131], v[134:135]
	v_pk_mul_f32 v[134:135], v[88:89], v[88:89]
	v_pk_mul_f32 v[130:131], v[132:133], v[130:131]
	v_pk_mul_f32 v[134:135], v[134:135], s[0:1] op_sel_hi:[1,0]
	v_pk_mul_f32 v[132:133], v[46:47], v[130:131]
	v_pk_fma_f32 v[130:131], v[46:47], v[130:131], v[46:47] neg_lo:[1,0,0] neg_hi:[1,0,0]
	v_exp_f32_e32 v134, v134
	v_cndmask_b32_e32 v46, v130, v132, vcc
	v_cmp_gt_f32_e32 vcc, 0, v47
	v_and_b32_e32 v130, 0x7fffffff, v88
	v_exp_f32_e32 v135, v135
	v_cndmask_b32_e32 v47, v131, v133, vcc
	v_and_b32_e32 v131, 0x7fffffff, v89
	v_pk_fma_f32 v[130:131], v[130:131], s[62:63], 1.0 op_sel_hi:[1,0,0]
	v_cmp_gt_f32_e32 vcc, 0, v88
	v_rcp_f32_e32 v130, v130
	v_rcp_f32_e32 v131, v131
	s_nop 0
	v_pk_fma_f32 v[132:133], v[130:131], s[92:93], v[128:129] op_sel_hi:[1,0,0]
	s_nop 0
	v_pk_fma_f32 v[132:133], v[130:131], v[132:133], s[94:95] op_sel_hi:[1,1,0]
	s_nop 0
	v_pk_fma_f32 v[132:133], v[130:131], v[132:133], s[96:97] op_sel_hi:[1,1,0]
	s_nop 0
	v_pk_fma_f32 v[132:133], v[130:131], v[132:133], s[74:75] op_sel_hi:[1,1,0]
	s_nop 0
	v_pk_mul_f32 v[130:131], v[130:131], v[132:133]
	v_pk_mul_f32 v[132:133], v[90:91], v[90:91]
	v_pk_mul_f32 v[130:131], v[134:135], v[130:131]
	v_pk_mul_f32 v[132:133], v[132:133], s[0:1] op_sel_hi:[1,0]
	v_pk_mul_f32 v[134:135], v[88:89], v[130:131]
	v_pk_fma_f32 v[130:131], v[88:89], v[130:131], v[88:89] neg_lo:[1,0,0] neg_hi:[1,0,0]
	v_exp_f32_e32 v132, v132
	v_cndmask_b32_e32 v88, v130, v134, vcc
	v_cmp_gt_f32_e32 vcc, 0, v89
	v_and_b32_e32 v130, 0x7fffffff, v90
	v_exp_f32_e32 v133, v133
	v_cndmask_b32_e32 v89, v131, v135, vcc
	v_and_b32_e32 v131, 0x7fffffff, v91
	v_pk_fma_f32 v[130:131], v[130:131], s[62:63], 1.0 op_sel_hi:[1,0,0]
	v_cmp_gt_f32_e32 vcc, 0, v90
	v_rcp_f32_e32 v130, v130
	v_rcp_f32_e32 v131, v131
	s_nop 0
	v_pk_fma_f32 v[134:135], v[130:131], s[92:93], v[128:129] op_sel_hi:[1,0,0]
	s_nop 0
	v_pk_fma_f32 v[134:135], v[130:131], v[134:135], s[94:95] op_sel_hi:[1,1,0]
	s_nop 0
	v_pk_fma_f32 v[134:135], v[130:131], v[134:135], s[96:97] op_sel_hi:[1,1,0]
	s_nop 0
	v_pk_fma_f32 v[134:135], v[130:131], v[134:135], s[74:75] op_sel_hi:[1,1,0]
	s_nop 0
	v_pk_mul_f32 v[130:131], v[130:131], v[134:135]
	v_pk_mul_f32 v[134:135], v[120:121], v[120:121]
	v_pk_mul_f32 v[130:131], v[132:133], v[130:131]
	v_pk_mul_f32 v[134:135], v[134:135], s[0:1] op_sel_hi:[1,0]
	v_pk_mul_f32 v[132:133], v[90:91], v[130:131]
	v_pk_fma_f32 v[130:131], v[90:91], v[130:131], v[90:91] neg_lo:[1,0,0] neg_hi:[1,0,0]
	v_exp_f32_e32 v134, v134
	v_cndmask_b32_e32 v90, v130, v132, vcc
	v_cmp_gt_f32_e32 vcc, 0, v91
	v_and_b32_e32 v130, 0x7fffffff, v120
	v_exp_f32_e32 v135, v135
	v_cndmask_b32_e32 v91, v131, v133, vcc
	v_and_b32_e32 v131, 0x7fffffff, v121
	v_pk_fma_f32 v[130:131], v[130:131], s[62:63], 1.0 op_sel_hi:[1,0,0]
	v_cmp_gt_f32_e32 vcc, 0, v120
	v_rcp_f32_e32 v130, v130
	v_rcp_f32_e32 v131, v131
	s_nop 0
	v_pk_fma_f32 v[132:133], v[130:131], s[92:93], v[128:129] op_sel_hi:[1,0,0]
	s_nop 0
	v_pk_fma_f32 v[132:133], v[130:131], v[132:133], s[94:95] op_sel_hi:[1,1,0]
	s_nop 0
	v_pk_fma_f32 v[132:133], v[130:131], v[132:133], s[96:97] op_sel_hi:[1,1,0]
	s_nop 0
	v_pk_fma_f32 v[132:133], v[130:131], v[132:133], s[74:75] op_sel_hi:[1,1,0]
	s_nop 0
	v_pk_mul_f32 v[130:131], v[130:131], v[132:133]
	v_pk_mul_f32 v[132:133], v[122:123], v[122:123]
	v_pk_mul_f32 v[130:131], v[134:135], v[130:131]
	v_pk_mul_f32 v[132:133], v[132:133], s[0:1] op_sel_hi:[1,0]
	v_pk_mul_f32 v[134:135], v[120:121], v[130:131]
	v_pk_fma_f32 v[130:131], v[120:121], v[130:131], v[120:121] neg_lo:[1,0,0] neg_hi:[1,0,0]
	v_exp_f32_e32 v132, v132
	v_cndmask_b32_e32 v120, v130, v134, vcc
	v_cmp_gt_f32_e32 vcc, 0, v121
	v_and_b32_e32 v130, 0x7fffffff, v122
	v_exp_f32_e32 v133, v133
	v_cndmask_b32_e32 v121, v131, v135, vcc
	v_and_b32_e32 v131, 0x7fffffff, v123
	v_pk_fma_f32 v[130:131], v[130:131], s[62:63], 1.0 op_sel_hi:[1,0,0]
	v_cmp_gt_f32_e32 vcc, 0, v122
	v_rcp_f32_e32 v130, v130
	v_rcp_f32_e32 v131, v131
	s_nop 0
	v_pk_fma_f32 v[134:135], v[130:131], s[92:93], v[128:129] op_sel_hi:[1,0,0]
	s_nop 0
	v_pk_fma_f32 v[134:135], v[130:131], v[134:135], s[94:95] op_sel_hi:[1,1,0]
	s_nop 0
	v_pk_fma_f32 v[134:135], v[130:131], v[134:135], s[96:97] op_sel_hi:[1,1,0]
	s_nop 0
	v_pk_fma_f32 v[134:135], v[130:131], v[134:135], s[74:75] op_sel_hi:[1,1,0]
	s_nop 0
	v_pk_mul_f32 v[130:131], v[130:131], v[134:135]
	v_pk_mul_f32 v[134:135], v[84:85], v[84:85]
	v_pk_mul_f32 v[130:131], v[132:133], v[130:131]
	v_pk_mul_f32 v[134:135], v[134:135], s[0:1] op_sel_hi:[1,0]
	v_pk_mul_f32 v[132:133], v[122:123], v[130:131]
	v_pk_fma_f32 v[130:131], v[122:123], v[130:131], v[122:123] neg_lo:[1,0,0] neg_hi:[1,0,0]
	v_exp_f32_e32 v134, v134
	v_cndmask_b32_e32 v122, v130, v132, vcc
	v_cmp_gt_f32_e32 vcc, 0, v123
	v_and_b32_e32 v130, 0x7fffffff, v84
	v_exp_f32_e32 v135, v135
	v_cndmask_b32_e32 v123, v131, v133, vcc
	v_and_b32_e32 v131, 0x7fffffff, v85
	v_pk_fma_f32 v[130:131], v[130:131], s[62:63], 1.0 op_sel_hi:[1,0,0]
	v_cmp_gt_f32_e32 vcc, 0, v84
	v_rcp_f32_e32 v130, v130
	v_rcp_f32_e32 v131, v131
	s_nop 0
	v_pk_fma_f32 v[132:133], v[130:131], s[92:93], v[128:129] op_sel_hi:[1,0,0]
	s_nop 0
	v_pk_fma_f32 v[132:133], v[130:131], v[132:133], s[94:95] op_sel_hi:[1,1,0]
	s_nop 0
	v_pk_fma_f32 v[132:133], v[130:131], v[132:133], s[96:97] op_sel_hi:[1,1,0]
	s_nop 0
	v_pk_fma_f32 v[132:133], v[130:131], v[132:133], s[74:75] op_sel_hi:[1,1,0]
	s_nop 0
	v_pk_mul_f32 v[130:131], v[130:131], v[132:133]
	v_pk_mul_f32 v[132:133], v[86:87], v[86:87]
	v_pk_mul_f32 v[130:131], v[134:135], v[130:131]
	v_pk_mul_f32 v[132:133], v[132:133], s[0:1] op_sel_hi:[1,0]
	v_pk_mul_f32 v[134:135], v[84:85], v[130:131]
	v_pk_fma_f32 v[130:131], v[84:85], v[130:131], v[84:85] neg_lo:[1,0,0] neg_hi:[1,0,0]
	v_exp_f32_e32 v132, v132
	v_cndmask_b32_e32 v84, v130, v134, vcc
	v_cmp_gt_f32_e32 vcc, 0, v85
	v_and_b32_e32 v130, 0x7fffffff, v86
	v_exp_f32_e32 v133, v133
	v_cndmask_b32_e32 v85, v131, v135, vcc
	v_and_b32_e32 v131, 0x7fffffff, v87
	v_pk_fma_f32 v[130:131], v[130:131], s[62:63], 1.0 op_sel_hi:[1,0,0]
	v_cmp_gt_f32_e32 vcc, 0, v86
	v_rcp_f32_e32 v130, v130
	v_rcp_f32_e32 v131, v131
	s_nop 0
	v_pk_fma_f32 v[134:135], v[130:131], s[92:93], v[128:129] op_sel_hi:[1,0,0]
	s_nop 0
	v_pk_fma_f32 v[134:135], v[130:131], v[134:135], s[94:95] op_sel_hi:[1,1,0]
	s_nop 0
	v_pk_fma_f32 v[134:135], v[130:131], v[134:135], s[96:97] op_sel_hi:[1,1,0]
	s_nop 0
	v_pk_fma_f32 v[134:135], v[130:131], v[134:135], s[74:75] op_sel_hi:[1,1,0]
	s_nop 0
	v_pk_mul_f32 v[130:131], v[130:131], v[134:135]
	v_pk_mul_f32 v[134:135], v[116:117], v[116:117]
	v_pk_mul_f32 v[130:131], v[132:133], v[130:131]
	v_pk_mul_f32 v[134:135], v[134:135], s[0:1] op_sel_hi:[1,0]
	v_pk_mul_f32 v[132:133], v[86:87], v[130:131]
	v_pk_fma_f32 v[130:131], v[86:87], v[130:131], v[86:87] neg_lo:[1,0,0] neg_hi:[1,0,0]
	v_exp_f32_e32 v134, v134
	v_cndmask_b32_e32 v86, v130, v132, vcc
	v_cmp_gt_f32_e32 vcc, 0, v87
	v_and_b32_e32 v130, 0x7fffffff, v116
	v_exp_f32_e32 v135, v135
	v_cndmask_b32_e32 v87, v131, v133, vcc
	v_and_b32_e32 v131, 0x7fffffff, v117
	v_pk_fma_f32 v[130:131], v[130:131], s[62:63], 1.0 op_sel_hi:[1,0,0]
	v_cmp_gt_f32_e32 vcc, 0, v116
	v_rcp_f32_e32 v130, v130
	v_rcp_f32_e32 v131, v131
	s_nop 0
	v_pk_fma_f32 v[132:133], v[130:131], s[92:93], v[128:129] op_sel_hi:[1,0,0]
	s_nop 0
	v_pk_fma_f32 v[132:133], v[130:131], v[132:133], s[94:95] op_sel_hi:[1,1,0]
	s_nop 0
	v_pk_fma_f32 v[132:133], v[130:131], v[132:133], s[96:97] op_sel_hi:[1,1,0]
	s_nop 0
	v_pk_fma_f32 v[132:133], v[130:131], v[132:133], s[74:75] op_sel_hi:[1,1,0]
	s_nop 0
	v_pk_mul_f32 v[130:131], v[130:131], v[132:133]
	v_pk_mul_f32 v[132:133], v[118:119], v[118:119]
	v_pk_mul_f32 v[130:131], v[134:135], v[130:131]
	v_pk_mul_f32 v[132:133], v[132:133], s[0:1] op_sel_hi:[1,0]
	v_pk_mul_f32 v[134:135], v[116:117], v[130:131]
	v_pk_fma_f32 v[130:131], v[116:117], v[130:131], v[116:117] neg_lo:[1,0,0] neg_hi:[1,0,0]
	v_exp_f32_e32 v132, v132
	v_cndmask_b32_e32 v116, v130, v134, vcc
	v_cmp_gt_f32_e32 vcc, 0, v117
	v_and_b32_e32 v130, 0x7fffffff, v118
	v_exp_f32_e32 v133, v133
	v_cndmask_b32_e32 v117, v131, v135, vcc
	v_and_b32_e32 v131, 0x7fffffff, v119
	v_pk_fma_f32 v[130:131], v[130:131], s[62:63], 1.0 op_sel_hi:[1,0,0]
	v_cmp_gt_f32_e32 vcc, 0, v118
	v_rcp_f32_e32 v130, v130
	v_rcp_f32_e32 v131, v131
	s_nop 0
	v_pk_fma_f32 v[134:135], v[130:131], s[92:93], v[128:129] op_sel_hi:[1,0,0]
	s_nop 0
	v_pk_fma_f32 v[134:135], v[130:131], v[134:135], s[94:95] op_sel_hi:[1,1,0]
	s_nop 0
	v_pk_fma_f32 v[134:135], v[130:131], v[134:135], s[96:97] op_sel_hi:[1,1,0]
	s_nop 0
	v_pk_fma_f32 v[134:135], v[130:131], v[134:135], s[74:75] op_sel_hi:[1,1,0]
	s_nop 0
	v_pk_mul_f32 v[130:131], v[130:131], v[134:135]
	v_pk_mul_f32 v[134:135], v[80:81], v[80:81]
	v_pk_mul_f32 v[130:131], v[132:133], v[130:131]
	v_pk_mul_f32 v[134:135], v[134:135], s[0:1] op_sel_hi:[1,0]
	v_pk_mul_f32 v[132:133], v[118:119], v[130:131]
	v_pk_fma_f32 v[130:131], v[118:119], v[130:131], v[118:119] neg_lo:[1,0,0] neg_hi:[1,0,0]
	v_exp_f32_e32 v134, v134
	v_cndmask_b32_e32 v118, v130, v132, vcc
	v_cmp_gt_f32_e32 vcc, 0, v119
	v_and_b32_e32 v130, 0x7fffffff, v80
	v_exp_f32_e32 v135, v135
	v_cndmask_b32_e32 v119, v131, v133, vcc
	v_and_b32_e32 v131, 0x7fffffff, v81
	v_pk_fma_f32 v[130:131], v[130:131], s[62:63], 1.0 op_sel_hi:[1,0,0]
	v_cmp_gt_f32_e32 vcc, 0, v80
	v_rcp_f32_e32 v130, v130
	v_rcp_f32_e32 v131, v131
	s_nop 0
	v_pk_fma_f32 v[132:133], v[130:131], s[92:93], v[128:129] op_sel_hi:[1,0,0]
	s_nop 0
	v_pk_fma_f32 v[132:133], v[130:131], v[132:133], s[94:95] op_sel_hi:[1,1,0]
	s_nop 0
	v_pk_fma_f32 v[132:133], v[130:131], v[132:133], s[96:97] op_sel_hi:[1,1,0]
	s_nop 0
	v_pk_fma_f32 v[132:133], v[130:131], v[132:133], s[74:75] op_sel_hi:[1,1,0]
	s_nop 0
	v_pk_mul_f32 v[130:131], v[130:131], v[132:133]
	v_pk_mul_f32 v[132:133], v[82:83], v[82:83]
	v_pk_mul_f32 v[130:131], v[134:135], v[130:131]
	v_pk_mul_f32 v[132:133], v[132:133], s[0:1] op_sel_hi:[1,0]
	v_pk_mul_f32 v[134:135], v[80:81], v[130:131]
	v_pk_fma_f32 v[130:131], v[80:81], v[130:131], v[80:81] neg_lo:[1,0,0] neg_hi:[1,0,0]
	v_exp_f32_e32 v132, v132
	v_cndmask_b32_e32 v80, v130, v134, vcc
	v_cmp_gt_f32_e32 vcc, 0, v81
	v_and_b32_e32 v130, 0x7fffffff, v82
	v_exp_f32_e32 v133, v133
	v_cndmask_b32_e32 v81, v131, v135, vcc
	v_and_b32_e32 v131, 0x7fffffff, v83
	v_pk_fma_f32 v[130:131], v[130:131], s[62:63], 1.0 op_sel_hi:[1,0,0]
	v_cmp_gt_f32_e32 vcc, 0, v82
	v_rcp_f32_e32 v130, v130
	v_rcp_f32_e32 v131, v131
	s_nop 0
	v_pk_fma_f32 v[134:135], v[130:131], s[92:93], v[128:129] op_sel_hi:[1,0,0]
	s_nop 0
	v_pk_fma_f32 v[134:135], v[130:131], v[134:135], s[94:95] op_sel_hi:[1,1,0]
	s_nop 0
	v_pk_fma_f32 v[134:135], v[130:131], v[134:135], s[96:97] op_sel_hi:[1,1,0]
	s_nop 0
	v_pk_fma_f32 v[134:135], v[130:131], v[134:135], s[74:75] op_sel_hi:[1,1,0]
	s_nop 0
	v_pk_mul_f32 v[130:131], v[130:131], v[134:135]
	v_pk_mul_f32 v[134:135], v[112:113], v[112:113]
	v_pk_mul_f32 v[130:131], v[132:133], v[130:131]
	v_pk_mul_f32 v[134:135], v[134:135], s[0:1] op_sel_hi:[1,0]
	v_pk_mul_f32 v[132:133], v[82:83], v[130:131]
	v_pk_fma_f32 v[130:131], v[82:83], v[130:131], v[82:83] neg_lo:[1,0,0] neg_hi:[1,0,0]
	v_exp_f32_e32 v134, v134
	v_cndmask_b32_e32 v82, v130, v132, vcc
	v_cmp_gt_f32_e32 vcc, 0, v83
	v_and_b32_e32 v130, 0x7fffffff, v112
	v_exp_f32_e32 v135, v135
	v_cndmask_b32_e32 v83, v131, v133, vcc
	v_and_b32_e32 v131, 0x7fffffff, v113
	v_pk_fma_f32 v[130:131], v[130:131], s[62:63], 1.0 op_sel_hi:[1,0,0]
	v_cmp_gt_f32_e32 vcc, 0, v112
	v_rcp_f32_e32 v130, v130
	v_rcp_f32_e32 v131, v131
	s_nop 0
	v_pk_fma_f32 v[132:133], v[130:131], s[92:93], v[128:129] op_sel_hi:[1,0,0]
	s_nop 0
	v_pk_fma_f32 v[132:133], v[130:131], v[132:133], s[94:95] op_sel_hi:[1,1,0]
	s_nop 0
	v_pk_fma_f32 v[132:133], v[130:131], v[132:133], s[96:97] op_sel_hi:[1,1,0]
	s_nop 0
	v_pk_fma_f32 v[132:133], v[130:131], v[132:133], s[74:75] op_sel_hi:[1,1,0]
	s_nop 0
	v_pk_mul_f32 v[130:131], v[130:131], v[132:133]
	v_pk_mul_f32 v[132:133], v[114:115], v[114:115]
	v_pk_mul_f32 v[130:131], v[134:135], v[130:131]
	v_pk_mul_f32 v[132:133], v[132:133], s[0:1] op_sel_hi:[1,0]
	v_pk_mul_f32 v[134:135], v[112:113], v[130:131]
	v_pk_fma_f32 v[130:131], v[112:113], v[130:131], v[112:113] neg_lo:[1,0,0] neg_hi:[1,0,0]
	v_exp_f32_e32 v132, v132
	v_cndmask_b32_e32 v112, v130, v134, vcc
	v_cmp_gt_f32_e32 vcc, 0, v113
	v_and_b32_e32 v130, 0x7fffffff, v114
	v_exp_f32_e32 v133, v133
	v_cndmask_b32_e32 v113, v131, v135, vcc
	v_and_b32_e32 v131, 0x7fffffff, v115
	v_pk_fma_f32 v[130:131], v[130:131], s[62:63], 1.0 op_sel_hi:[1,0,0]
	v_cmp_gt_f32_e32 vcc, 0, v114
	v_rcp_f32_e32 v130, v130
	v_rcp_f32_e32 v131, v131
	s_nop 0
	v_pk_fma_f32 v[134:135], v[130:131], s[92:93], v[128:129] op_sel_hi:[1,0,0]
	s_nop 0
	v_pk_fma_f32 v[134:135], v[130:131], v[134:135], s[94:95] op_sel_hi:[1,1,0]
	s_nop 0
	v_pk_fma_f32 v[134:135], v[130:131], v[134:135], s[96:97] op_sel_hi:[1,1,0]
	s_nop 0
	v_pk_fma_f32 v[134:135], v[130:131], v[134:135], s[74:75] op_sel_hi:[1,1,0]
	s_nop 0
	v_pk_mul_f32 v[130:131], v[130:131], v[134:135]
	v_pk_mul_f32 v[134:135], v[76:77], v[76:77]
	v_pk_mul_f32 v[130:131], v[132:133], v[130:131]
	v_pk_mul_f32 v[134:135], v[134:135], s[0:1] op_sel_hi:[1,0]
	v_pk_mul_f32 v[132:133], v[114:115], v[130:131]
	v_pk_fma_f32 v[130:131], v[114:115], v[130:131], v[114:115] neg_lo:[1,0,0] neg_hi:[1,0,0]
	v_exp_f32_e32 v134, v134
	v_cndmask_b32_e32 v114, v130, v132, vcc
	v_cmp_gt_f32_e32 vcc, 0, v115
	v_and_b32_e32 v130, 0x7fffffff, v76
	v_exp_f32_e32 v135, v135
	v_cndmask_b32_e32 v115, v131, v133, vcc
	v_and_b32_e32 v131, 0x7fffffff, v77
	v_pk_fma_f32 v[130:131], v[130:131], s[62:63], 1.0 op_sel_hi:[1,0,0]
	v_cmp_gt_f32_e32 vcc, 0, v76
	v_rcp_f32_e32 v130, v130
	v_rcp_f32_e32 v131, v131
	s_nop 0
	v_pk_fma_f32 v[132:133], v[130:131], s[92:93], v[128:129] op_sel_hi:[1,0,0]
	s_nop 0
	v_pk_fma_f32 v[132:133], v[130:131], v[132:133], s[94:95] op_sel_hi:[1,1,0]
	s_nop 0
	v_pk_fma_f32 v[132:133], v[130:131], v[132:133], s[96:97] op_sel_hi:[1,1,0]
	s_nop 0
	v_pk_fma_f32 v[132:133], v[130:131], v[132:133], s[74:75] op_sel_hi:[1,1,0]
	s_nop 0
	v_pk_mul_f32 v[130:131], v[130:131], v[132:133]
	v_pk_mul_f32 v[132:133], v[78:79], v[78:79]
	v_pk_mul_f32 v[130:131], v[134:135], v[130:131]
	v_pk_mul_f32 v[132:133], v[132:133], s[0:1] op_sel_hi:[1,0]
	v_pk_mul_f32 v[134:135], v[76:77], v[130:131]
	v_pk_fma_f32 v[130:131], v[76:77], v[130:131], v[76:77] neg_lo:[1,0,0] neg_hi:[1,0,0]
	v_exp_f32_e32 v132, v132
	v_cndmask_b32_e32 v76, v130, v134, vcc
	v_cmp_gt_f32_e32 vcc, 0, v77
	v_and_b32_e32 v130, 0x7fffffff, v78
	v_exp_f32_e32 v133, v133
	v_cndmask_b32_e32 v77, v131, v135, vcc
	v_and_b32_e32 v131, 0x7fffffff, v79
	v_pk_fma_f32 v[130:131], v[130:131], s[62:63], 1.0 op_sel_hi:[1,0,0]
	v_cmp_gt_f32_e32 vcc, 0, v78
	v_rcp_f32_e32 v130, v130
	v_rcp_f32_e32 v131, v131
	s_nop 0
	v_pk_fma_f32 v[134:135], v[130:131], s[92:93], v[128:129] op_sel_hi:[1,0,0]
	s_nop 0
	v_pk_fma_f32 v[134:135], v[130:131], v[134:135], s[94:95] op_sel_hi:[1,1,0]
	s_nop 0
	v_pk_fma_f32 v[134:135], v[130:131], v[134:135], s[96:97] op_sel_hi:[1,1,0]
	s_nop 0
	v_pk_fma_f32 v[134:135], v[130:131], v[134:135], s[74:75] op_sel_hi:[1,1,0]
	s_nop 0
	v_pk_mul_f32 v[130:131], v[130:131], v[134:135]
	v_pk_mul_f32 v[134:135], v[108:109], v[108:109]
	v_pk_mul_f32 v[130:131], v[132:133], v[130:131]
	v_pk_mul_f32 v[134:135], v[134:135], s[0:1] op_sel_hi:[1,0]
	v_pk_mul_f32 v[132:133], v[78:79], v[130:131]
	v_pk_fma_f32 v[130:131], v[78:79], v[130:131], v[78:79] neg_lo:[1,0,0] neg_hi:[1,0,0]
	v_exp_f32_e32 v134, v134
	v_cndmask_b32_e32 v78, v130, v132, vcc
	v_cmp_gt_f32_e32 vcc, 0, v79
	v_and_b32_e32 v130, 0x7fffffff, v108
	v_exp_f32_e32 v135, v135
	v_cndmask_b32_e32 v79, v131, v133, vcc
	v_and_b32_e32 v131, 0x7fffffff, v109
	v_pk_fma_f32 v[130:131], v[130:131], s[62:63], 1.0 op_sel_hi:[1,0,0]
	v_cmp_gt_f32_e32 vcc, 0, v108
	v_rcp_f32_e32 v130, v130
	v_rcp_f32_e32 v131, v131
	s_nop 0
	v_pk_fma_f32 v[132:133], v[130:131], s[92:93], v[128:129] op_sel_hi:[1,0,0]
	s_nop 0
	v_pk_fma_f32 v[132:133], v[130:131], v[132:133], s[94:95] op_sel_hi:[1,1,0]
	s_nop 0
	v_pk_fma_f32 v[132:133], v[130:131], v[132:133], s[96:97] op_sel_hi:[1,1,0]
	s_nop 0
	v_pk_fma_f32 v[132:133], v[130:131], v[132:133], s[74:75] op_sel_hi:[1,1,0]
	s_nop 0
	v_pk_mul_f32 v[130:131], v[130:131], v[132:133]
	v_pk_mul_f32 v[132:133], v[110:111], v[110:111]
	v_pk_mul_f32 v[130:131], v[134:135], v[130:131]
	v_pk_mul_f32 v[132:133], v[132:133], s[0:1] op_sel_hi:[1,0]
	v_pk_mul_f32 v[134:135], v[108:109], v[130:131]
	v_pk_fma_f32 v[130:131], v[108:109], v[130:131], v[108:109] neg_lo:[1,0,0] neg_hi:[1,0,0]
	v_exp_f32_e32 v132, v132
	v_cndmask_b32_e32 v108, v130, v134, vcc
	v_cmp_gt_f32_e32 vcc, 0, v109
	v_and_b32_e32 v130, 0x7fffffff, v110
	v_exp_f32_e32 v133, v133
	v_cndmask_b32_e32 v109, v131, v135, vcc
	v_and_b32_e32 v131, 0x7fffffff, v111
	v_pk_fma_f32 v[130:131], v[130:131], s[62:63], 1.0 op_sel_hi:[1,0,0]
	v_cmp_gt_f32_e32 vcc, 0, v110
	v_rcp_f32_e32 v130, v130
	v_rcp_f32_e32 v131, v131
	s_nop 0
	v_pk_fma_f32 v[134:135], v[130:131], s[92:93], v[128:129] op_sel_hi:[1,0,0]
	s_nop 0
	v_pk_fma_f32 v[134:135], v[130:131], v[134:135], s[94:95] op_sel_hi:[1,1,0]
	s_nop 0
	v_pk_fma_f32 v[134:135], v[130:131], v[134:135], s[96:97] op_sel_hi:[1,1,0]
	s_nop 0
	v_pk_fma_f32 v[134:135], v[130:131], v[134:135], s[74:75] op_sel_hi:[1,1,0]
	s_nop 0
	v_pk_mul_f32 v[130:131], v[130:131], v[134:135]
	v_pk_mul_f32 v[134:135], v[20:21], v[20:21]
	v_pk_mul_f32 v[130:131], v[132:133], v[130:131]
	v_pk_mul_f32 v[134:135], v[134:135], s[0:1] op_sel_hi:[1,0]
	v_pk_mul_f32 v[132:133], v[110:111], v[130:131]
	v_pk_fma_f32 v[130:131], v[110:111], v[130:131], v[110:111] neg_lo:[1,0,0] neg_hi:[1,0,0]
	v_exp_f32_e32 v134, v134
	v_cndmask_b32_e32 v110, v130, v132, vcc
	v_cmp_gt_f32_e32 vcc, 0, v111
	v_and_b32_e32 v130, 0x7fffffff, v20
	v_exp_f32_e32 v135, v135
	v_cndmask_b32_e32 v111, v131, v133, vcc
	v_and_b32_e32 v131, 0x7fffffff, v21
	v_pk_fma_f32 v[130:131], v[130:131], s[62:63], 1.0 op_sel_hi:[1,0,0]
	v_cmp_gt_f32_e32 vcc, 0, v20
	v_rcp_f32_e32 v130, v130
	v_rcp_f32_e32 v131, v131
	s_nop 0
	v_pk_fma_f32 v[132:133], v[130:131], s[92:93], v[128:129] op_sel_hi:[1,0,0]
	s_nop 0
	v_pk_fma_f32 v[132:133], v[130:131], v[132:133], s[94:95] op_sel_hi:[1,1,0]
	s_nop 0
	v_pk_fma_f32 v[132:133], v[130:131], v[132:133], s[96:97] op_sel_hi:[1,1,0]
	s_nop 0
	v_pk_fma_f32 v[132:133], v[130:131], v[132:133], s[74:75] op_sel_hi:[1,1,0]
	s_nop 0
	v_pk_mul_f32 v[130:131], v[130:131], v[132:133]
	v_pk_mul_f32 v[132:133], v[22:23], v[22:23]
	v_pk_mul_f32 v[130:131], v[134:135], v[130:131]
	v_pk_mul_f32 v[132:133], v[132:133], s[0:1] op_sel_hi:[1,0]
	v_pk_mul_f32 v[134:135], v[20:21], v[130:131]
	v_pk_fma_f32 v[130:131], v[20:21], v[130:131], v[20:21] neg_lo:[1,0,0] neg_hi:[1,0,0]
	v_exp_f32_e32 v132, v132
	v_cndmask_b32_e32 v20, v130, v134, vcc
	v_cmp_gt_f32_e32 vcc, 0, v21
	v_and_b32_e32 v130, 0x7fffffff, v22
	v_exp_f32_e32 v133, v133
	v_cndmask_b32_e32 v21, v131, v135, vcc
	v_and_b32_e32 v131, 0x7fffffff, v23
	v_pk_fma_f32 v[130:131], v[130:131], s[62:63], 1.0 op_sel_hi:[1,0,0]
	v_cmp_gt_f32_e32 vcc, 0, v22
	v_rcp_f32_e32 v130, v130
	v_rcp_f32_e32 v131, v131
	s_nop 0
	v_pk_fma_f32 v[134:135], v[130:131], s[92:93], v[128:129] op_sel_hi:[1,0,0]
	s_nop 0
	v_pk_fma_f32 v[134:135], v[130:131], v[134:135], s[94:95] op_sel_hi:[1,1,0]
	s_nop 0
	v_pk_fma_f32 v[134:135], v[130:131], v[134:135], s[96:97] op_sel_hi:[1,1,0]
	s_nop 0
	v_pk_fma_f32 v[134:135], v[130:131], v[134:135], s[74:75] op_sel_hi:[1,1,0]
	s_nop 0
	v_pk_mul_f32 v[130:131], v[130:131], v[134:135]
	v_pk_mul_f32 v[134:135], v[40:41], v[40:41]
	v_pk_mul_f32 v[130:131], v[132:133], v[130:131]
	v_pk_mul_f32 v[134:135], v[134:135], s[0:1] op_sel_hi:[1,0]
	v_pk_mul_f32 v[132:133], v[22:23], v[130:131]
	v_pk_fma_f32 v[130:131], v[22:23], v[130:131], v[22:23] neg_lo:[1,0,0] neg_hi:[1,0,0]
	v_exp_f32_e32 v134, v134
	v_cndmask_b32_e32 v22, v130, v132, vcc
	v_cmp_gt_f32_e32 vcc, 0, v23
	v_and_b32_e32 v130, 0x7fffffff, v40
	v_exp_f32_e32 v135, v135
	v_cndmask_b32_e32 v23, v131, v133, vcc
	v_and_b32_e32 v131, 0x7fffffff, v41
	v_pk_fma_f32 v[130:131], v[130:131], s[62:63], 1.0 op_sel_hi:[1,0,0]
	v_cmp_gt_f32_e32 vcc, 0, v40
	v_rcp_f32_e32 v130, v130
	v_rcp_f32_e32 v131, v131
	s_nop 0
	v_pk_fma_f32 v[132:133], v[130:131], s[92:93], v[128:129] op_sel_hi:[1,0,0]
	s_nop 0
	v_pk_fma_f32 v[132:133], v[130:131], v[132:133], s[94:95] op_sel_hi:[1,1,0]
	s_nop 0
	v_pk_fma_f32 v[132:133], v[130:131], v[132:133], s[96:97] op_sel_hi:[1,1,0]
	s_nop 0
	v_pk_fma_f32 v[132:133], v[130:131], v[132:133], s[74:75] op_sel_hi:[1,1,0]
	s_nop 0
	v_pk_mul_f32 v[130:131], v[130:131], v[132:133]
	v_pk_mul_f32 v[132:133], v[42:43], v[42:43]
	v_pk_mul_f32 v[130:131], v[134:135], v[130:131]
	v_pk_mul_f32 v[132:133], v[132:133], s[0:1] op_sel_hi:[1,0]
	v_pk_mul_f32 v[134:135], v[40:41], v[130:131]
	v_pk_fma_f32 v[130:131], v[40:41], v[130:131], v[40:41] neg_lo:[1,0,0] neg_hi:[1,0,0]
	v_exp_f32_e32 v132, v132
	v_cndmask_b32_e32 v40, v130, v134, vcc
	v_cmp_gt_f32_e32 vcc, 0, v41
	v_and_b32_e32 v130, 0x7fffffff, v42
	v_exp_f32_e32 v133, v133
	v_cndmask_b32_e32 v41, v131, v135, vcc
	v_and_b32_e32 v131, 0x7fffffff, v43
	v_pk_fma_f32 v[130:131], v[130:131], s[62:63], 1.0 op_sel_hi:[1,0,0]
	v_cmp_gt_f32_e32 vcc, 0, v42
	v_rcp_f32_e32 v130, v130
	v_rcp_f32_e32 v131, v131
	s_nop 0
	v_pk_fma_f32 v[134:135], v[130:131], s[92:93], v[128:129] op_sel_hi:[1,0,0]
	s_nop 0
	v_pk_fma_f32 v[134:135], v[130:131], v[134:135], s[94:95] op_sel_hi:[1,1,0]
	s_nop 0
	v_pk_fma_f32 v[134:135], v[130:131], v[134:135], s[96:97] op_sel_hi:[1,1,0]
	s_nop 0
	v_pk_fma_f32 v[134:135], v[130:131], v[134:135], s[74:75] op_sel_hi:[1,1,0]
	s_nop 0
	v_pk_mul_f32 v[130:131], v[130:131], v[134:135]
	v_pk_mul_f32 v[134:135], v[16:17], v[16:17]
	v_pk_mul_f32 v[130:131], v[132:133], v[130:131]
	v_pk_mul_f32 v[134:135], v[134:135], s[0:1] op_sel_hi:[1,0]
	v_pk_mul_f32 v[132:133], v[42:43], v[130:131]
	v_pk_fma_f32 v[130:131], v[42:43], v[130:131], v[42:43] neg_lo:[1,0,0] neg_hi:[1,0,0]
	v_exp_f32_e32 v134, v134
	v_cndmask_b32_e32 v42, v130, v132, vcc
	v_cmp_gt_f32_e32 vcc, 0, v43
	v_and_b32_e32 v130, 0x7fffffff, v16
	v_exp_f32_e32 v135, v135
	v_cndmask_b32_e32 v43, v131, v133, vcc
	v_and_b32_e32 v131, 0x7fffffff, v17
	v_pk_fma_f32 v[130:131], v[130:131], s[62:63], 1.0 op_sel_hi:[1,0,0]
	v_cmp_gt_f32_e32 vcc, 0, v16
	v_rcp_f32_e32 v130, v130
	v_rcp_f32_e32 v131, v131
	s_nop 0
	v_pk_fma_f32 v[132:133], v[130:131], s[92:93], v[128:129] op_sel_hi:[1,0,0]
	s_nop 0
	v_pk_fma_f32 v[132:133], v[130:131], v[132:133], s[94:95] op_sel_hi:[1,1,0]
	s_nop 0
	v_pk_fma_f32 v[132:133], v[130:131], v[132:133], s[96:97] op_sel_hi:[1,1,0]
	s_nop 0
	v_pk_fma_f32 v[132:133], v[130:131], v[132:133], s[74:75] op_sel_hi:[1,1,0]
	s_nop 0
	v_pk_mul_f32 v[130:131], v[130:131], v[132:133]
	v_pk_mul_f32 v[132:133], v[18:19], v[18:19]
	v_pk_mul_f32 v[130:131], v[134:135], v[130:131]
	v_pk_mul_f32 v[132:133], v[132:133], s[0:1] op_sel_hi:[1,0]
	v_pk_mul_f32 v[134:135], v[16:17], v[130:131]
	v_pk_fma_f32 v[130:131], v[16:17], v[130:131], v[16:17] neg_lo:[1,0,0] neg_hi:[1,0,0]
	v_exp_f32_e32 v132, v132
	v_cndmask_b32_e32 v16, v130, v134, vcc
	v_cmp_gt_f32_e32 vcc, 0, v17
	v_and_b32_e32 v130, 0x7fffffff, v18
	v_exp_f32_e32 v133, v133
	v_cndmask_b32_e32 v17, v131, v135, vcc
	v_and_b32_e32 v131, 0x7fffffff, v19
	v_pk_fma_f32 v[130:131], v[130:131], s[62:63], 1.0 op_sel_hi:[1,0,0]
	v_cmp_gt_f32_e32 vcc, 0, v18
	v_rcp_f32_e32 v130, v130
	v_rcp_f32_e32 v131, v131
	s_nop 0
	v_pk_fma_f32 v[134:135], v[130:131], s[92:93], v[128:129] op_sel_hi:[1,0,0]
	s_nop 0
	v_pk_fma_f32 v[134:135], v[130:131], v[134:135], s[94:95] op_sel_hi:[1,1,0]
	s_nop 0
	v_pk_fma_f32 v[134:135], v[130:131], v[134:135], s[96:97] op_sel_hi:[1,1,0]
	s_nop 0
	v_pk_fma_f32 v[134:135], v[130:131], v[134:135], s[74:75] op_sel_hi:[1,1,0]
	s_nop 0
	v_pk_mul_f32 v[130:131], v[130:131], v[134:135]
	v_pk_mul_f32 v[134:135], v[36:37], v[36:37]
	v_pk_mul_f32 v[130:131], v[132:133], v[130:131]
	v_pk_mul_f32 v[134:135], v[134:135], s[0:1] op_sel_hi:[1,0]
	v_pk_mul_f32 v[132:133], v[18:19], v[130:131]
	v_pk_fma_f32 v[130:131], v[18:19], v[130:131], v[18:19] neg_lo:[1,0,0] neg_hi:[1,0,0]
	v_exp_f32_e32 v134, v134
	v_cndmask_b32_e32 v18, v130, v132, vcc
	v_cmp_gt_f32_e32 vcc, 0, v19
	v_and_b32_e32 v130, 0x7fffffff, v36
	v_exp_f32_e32 v135, v135
	v_cndmask_b32_e32 v19, v131, v133, vcc
	v_and_b32_e32 v131, 0x7fffffff, v37
	v_pk_fma_f32 v[130:131], v[130:131], s[62:63], 1.0 op_sel_hi:[1,0,0]
	v_cmp_gt_f32_e32 vcc, 0, v36
	v_rcp_f32_e32 v130, v130
	v_rcp_f32_e32 v131, v131
	s_nop 0
	v_pk_fma_f32 v[132:133], v[130:131], s[92:93], v[128:129] op_sel_hi:[1,0,0]
	s_nop 0
	v_pk_fma_f32 v[132:133], v[130:131], v[132:133], s[94:95] op_sel_hi:[1,1,0]
	s_nop 0
	v_pk_fma_f32 v[132:133], v[130:131], v[132:133], s[96:97] op_sel_hi:[1,1,0]
	s_nop 0
	v_pk_fma_f32 v[132:133], v[130:131], v[132:133], s[74:75] op_sel_hi:[1,1,0]
	s_nop 0
	v_pk_mul_f32 v[130:131], v[130:131], v[132:133]
	v_pk_mul_f32 v[132:133], v[38:39], v[38:39]
	v_pk_mul_f32 v[130:131], v[134:135], v[130:131]
	v_pk_mul_f32 v[132:133], v[132:133], s[0:1] op_sel_hi:[1,0]
	v_pk_mul_f32 v[134:135], v[36:37], v[130:131]
	v_pk_fma_f32 v[130:131], v[36:37], v[130:131], v[36:37] neg_lo:[1,0,0] neg_hi:[1,0,0]
	v_exp_f32_e32 v132, v132
	v_cndmask_b32_e32 v36, v130, v134, vcc
	v_cmp_gt_f32_e32 vcc, 0, v37
	v_and_b32_e32 v130, 0x7fffffff, v38
	v_exp_f32_e32 v133, v133
	v_cndmask_b32_e32 v37, v131, v135, vcc
	v_and_b32_e32 v131, 0x7fffffff, v39
	v_pk_fma_f32 v[130:131], v[130:131], s[62:63], 1.0 op_sel_hi:[1,0,0]
	v_cmp_gt_f32_e32 vcc, 0, v38
	v_rcp_f32_e32 v130, v130
	v_rcp_f32_e32 v131, v131
	s_nop 0
	v_pk_fma_f32 v[134:135], v[130:131], s[92:93], v[128:129] op_sel_hi:[1,0,0]
	s_nop 0
	v_pk_fma_f32 v[134:135], v[130:131], v[134:135], s[94:95] op_sel_hi:[1,1,0]
	s_nop 0
	v_pk_fma_f32 v[134:135], v[130:131], v[134:135], s[96:97] op_sel_hi:[1,1,0]
	s_nop 0
	v_pk_fma_f32 v[134:135], v[130:131], v[134:135], s[74:75] op_sel_hi:[1,1,0]
	s_nop 0
	v_pk_mul_f32 v[130:131], v[130:131], v[134:135]
	v_pk_mul_f32 v[134:135], v[24:25], v[24:25]
	v_pk_mul_f32 v[130:131], v[132:133], v[130:131]
	v_pk_mul_f32 v[134:135], v[134:135], s[0:1] op_sel_hi:[1,0]
	v_pk_mul_f32 v[132:133], v[38:39], v[130:131]
	v_pk_fma_f32 v[130:131], v[38:39], v[130:131], v[38:39] neg_lo:[1,0,0] neg_hi:[1,0,0]
	v_exp_f32_e32 v134, v134
	v_cndmask_b32_e32 v38, v130, v132, vcc
	v_cmp_gt_f32_e32 vcc, 0, v39
	v_and_b32_e32 v130, 0x7fffffff, v24
	v_exp_f32_e32 v135, v135
	v_cndmask_b32_e32 v39, v131, v133, vcc
	v_and_b32_e32 v131, 0x7fffffff, v25
	v_pk_fma_f32 v[130:131], v[130:131], s[62:63], 1.0 op_sel_hi:[1,0,0]
	v_cmp_gt_f32_e32 vcc, 0, v24
	v_rcp_f32_e32 v130, v130
	v_rcp_f32_e32 v131, v131
	s_nop 0
	v_pk_fma_f32 v[132:133], v[130:131], s[92:93], v[128:129] op_sel_hi:[1,0,0]
	s_nop 0
	v_pk_fma_f32 v[132:133], v[130:131], v[132:133], s[94:95] op_sel_hi:[1,1,0]
	s_nop 0
	v_pk_fma_f32 v[132:133], v[130:131], v[132:133], s[96:97] op_sel_hi:[1,1,0]
	s_nop 0
	v_pk_fma_f32 v[132:133], v[130:131], v[132:133], s[74:75] op_sel_hi:[1,1,0]
	s_nop 0
	v_pk_mul_f32 v[130:131], v[130:131], v[132:133]
	v_pk_mul_f32 v[132:133], v[26:27], v[26:27]
	v_pk_mul_f32 v[130:131], v[134:135], v[130:131]
	v_pk_mul_f32 v[132:133], v[132:133], s[0:1] op_sel_hi:[1,0]
	v_pk_mul_f32 v[134:135], v[24:25], v[130:131]
	v_pk_fma_f32 v[130:131], v[24:25], v[130:131], v[24:25] neg_lo:[1,0,0] neg_hi:[1,0,0]
	v_exp_f32_e32 v132, v132
	v_cndmask_b32_e32 v24, v130, v134, vcc
	v_cmp_gt_f32_e32 vcc, 0, v25
	v_and_b32_e32 v130, 0x7fffffff, v26
	v_exp_f32_e32 v133, v133
	v_cndmask_b32_e32 v25, v131, v135, vcc
	v_and_b32_e32 v131, 0x7fffffff, v27
	v_pk_fma_f32 v[130:131], v[130:131], s[62:63], 1.0 op_sel_hi:[1,0,0]
	v_cmp_gt_f32_e32 vcc, 0, v26
	v_rcp_f32_e32 v130, v130
	v_rcp_f32_e32 v131, v131
	s_nop 0
	v_pk_fma_f32 v[134:135], v[130:131], s[92:93], v[128:129] op_sel_hi:[1,0,0]
	s_nop 0
	v_pk_fma_f32 v[134:135], v[130:131], v[134:135], s[94:95] op_sel_hi:[1,1,0]
	s_nop 0
	v_pk_fma_f32 v[134:135], v[130:131], v[134:135], s[96:97] op_sel_hi:[1,1,0]
	s_nop 0
	v_pk_fma_f32 v[134:135], v[130:131], v[134:135], s[74:75] op_sel_hi:[1,1,0]
	s_nop 0
	v_pk_mul_f32 v[130:131], v[130:131], v[134:135]
	v_pk_mul_f32 v[134:135], v[32:33], v[32:33]
	v_pk_mul_f32 v[130:131], v[132:133], v[130:131]
	v_pk_mul_f32 v[134:135], v[134:135], s[0:1] op_sel_hi:[1,0]
	v_pk_mul_f32 v[132:133], v[26:27], v[130:131]
	v_pk_fma_f32 v[130:131], v[26:27], v[130:131], v[26:27] neg_lo:[1,0,0] neg_hi:[1,0,0]
	v_exp_f32_e32 v134, v134
	v_cndmask_b32_e32 v26, v130, v132, vcc
	v_cmp_gt_f32_e32 vcc, 0, v27
	v_and_b32_e32 v130, 0x7fffffff, v32
	v_exp_f32_e32 v135, v135
	v_cndmask_b32_e32 v27, v131, v133, vcc
	v_and_b32_e32 v131, 0x7fffffff, v33
	v_pk_fma_f32 v[130:131], v[130:131], s[62:63], 1.0 op_sel_hi:[1,0,0]
	v_cmp_gt_f32_e32 vcc, 0, v32
	v_rcp_f32_e32 v130, v130
	v_rcp_f32_e32 v131, v131
	s_nop 0
	v_pk_fma_f32 v[132:133], v[130:131], s[92:93], v[128:129] op_sel_hi:[1,0,0]
	s_nop 0
	v_pk_fma_f32 v[132:133], v[130:131], v[132:133], s[94:95] op_sel_hi:[1,1,0]
	s_nop 0
	v_pk_fma_f32 v[132:133], v[130:131], v[132:133], s[96:97] op_sel_hi:[1,1,0]
	s_nop 0
	v_pk_fma_f32 v[132:133], v[130:131], v[132:133], s[74:75] op_sel_hi:[1,1,0]
	s_nop 0
	v_pk_mul_f32 v[130:131], v[130:131], v[132:133]
	v_pk_mul_f32 v[132:133], v[34:35], v[34:35]
	v_pk_mul_f32 v[130:131], v[134:135], v[130:131]
	v_pk_mul_f32 v[132:133], v[132:133], s[0:1] op_sel_hi:[1,0]
	v_pk_mul_f32 v[134:135], v[32:33], v[130:131]
	v_pk_fma_f32 v[130:131], v[32:33], v[130:131], v[32:33] neg_lo:[1,0,0] neg_hi:[1,0,0]
	v_exp_f32_e32 v132, v132
	v_cndmask_b32_e32 v32, v130, v134, vcc
	v_cmp_gt_f32_e32 vcc, 0, v33
	v_and_b32_e32 v130, 0x7fffffff, v34
	v_exp_f32_e32 v133, v133
	v_cndmask_b32_e32 v33, v131, v135, vcc
	v_and_b32_e32 v131, 0x7fffffff, v35
	v_pk_fma_f32 v[130:131], v[130:131], s[62:63], 1.0 op_sel_hi:[1,0,0]
	v_cmp_gt_f32_e32 vcc, 0, v34
	v_rcp_f32_e32 v130, v130
	v_rcp_f32_e32 v131, v131
	s_nop 0
	v_pk_fma_f32 v[134:135], v[130:131], s[92:93], v[128:129] op_sel_hi:[1,0,0]
	s_nop 0
	v_pk_fma_f32 v[134:135], v[130:131], v[134:135], s[94:95] op_sel_hi:[1,1,0]
	s_nop 0
	v_pk_fma_f32 v[134:135], v[130:131], v[134:135], s[96:97] op_sel_hi:[1,1,0]
	s_nop 0
	v_pk_fma_f32 v[134:135], v[130:131], v[134:135], s[74:75] op_sel_hi:[1,1,0]
	s_nop 0
	v_pk_mul_f32 v[130:131], v[130:131], v[134:135]
	v_pk_mul_f32 v[134:135], v[28:29], v[28:29]
	v_pk_mul_f32 v[130:131], v[132:133], v[130:131]
	v_pk_mul_f32 v[134:135], v[134:135], s[0:1] op_sel_hi:[1,0]
	v_pk_mul_f32 v[132:133], v[34:35], v[130:131]
	v_pk_fma_f32 v[130:131], v[34:35], v[130:131], v[34:35] neg_lo:[1,0,0] neg_hi:[1,0,0]
	v_exp_f32_e32 v134, v134
	v_cndmask_b32_e32 v34, v130, v132, vcc
	v_cmp_gt_f32_e32 vcc, 0, v35
	v_and_b32_e32 v130, 0x7fffffff, v28
	v_exp_f32_e32 v135, v135
	v_cndmask_b32_e32 v35, v131, v133, vcc
	v_and_b32_e32 v131, 0x7fffffff, v29
	v_pk_fma_f32 v[130:131], v[130:131], s[62:63], 1.0 op_sel_hi:[1,0,0]
	v_cmp_gt_f32_e32 vcc, 0, v28
	v_rcp_f32_e32 v130, v130
	v_rcp_f32_e32 v131, v131
	s_nop 0
	v_pk_fma_f32 v[132:133], v[130:131], s[92:93], v[128:129] op_sel_hi:[1,0,0]
	s_nop 0
	v_pk_fma_f32 v[132:133], v[130:131], v[132:133], s[94:95] op_sel_hi:[1,1,0]
	s_nop 0
	v_pk_fma_f32 v[132:133], v[130:131], v[132:133], s[96:97] op_sel_hi:[1,1,0]
	s_nop 0
	v_pk_fma_f32 v[132:133], v[130:131], v[132:133], s[74:75] op_sel_hi:[1,1,0]
	s_nop 0
	v_pk_mul_f32 v[130:131], v[130:131], v[132:133]
	v_pk_mul_f32 v[132:133], v[30:31], v[30:31]
	v_pk_mul_f32 v[130:131], v[134:135], v[130:131]
	v_pk_mul_f32 v[132:133], v[132:133], s[0:1] op_sel_hi:[1,0]
	v_pk_mul_f32 v[134:135], v[28:29], v[130:131]
	v_pk_fma_f32 v[130:131], v[28:29], v[130:131], v[28:29] neg_lo:[1,0,0] neg_hi:[1,0,0]
	v_exp_f32_e32 v132, v132
	v_cndmask_b32_e32 v28, v130, v134, vcc
	v_cmp_gt_f32_e32 vcc, 0, v29
	v_and_b32_e32 v130, 0x7fffffff, v30
	v_exp_f32_e32 v133, v133
	v_cndmask_b32_e32 v29, v131, v135, vcc
	v_and_b32_e32 v131, 0x7fffffff, v31
	v_pk_fma_f32 v[130:131], v[130:131], s[62:63], 1.0 op_sel_hi:[1,0,0]
	v_cmp_gt_f32_e32 vcc, 0, v30
	v_rcp_f32_e32 v130, v130
	v_rcp_f32_e32 v131, v131
	s_nop 0
	v_pk_fma_f32 v[134:135], v[130:131], s[92:93], v[128:129] op_sel_hi:[1,0,0]
	s_nop 0
	v_pk_fma_f32 v[134:135], v[130:131], v[134:135], s[94:95] op_sel_hi:[1,1,0]
	s_nop 0
	v_pk_fma_f32 v[134:135], v[130:131], v[134:135], s[96:97] op_sel_hi:[1,1,0]
	s_nop 0
	v_pk_fma_f32 v[134:135], v[130:131], v[134:135], s[74:75] op_sel_hi:[1,1,0]
	s_nop 0
	v_pk_mul_f32 v[130:131], v[130:131], v[134:135]
	v_pk_mul_f32 v[134:135], v[60:61], v[60:61]
	v_pk_mul_f32 v[130:131], v[132:133], v[130:131]
	v_pk_mul_f32 v[134:135], v[134:135], s[0:1] op_sel_hi:[1,0]
	v_pk_mul_f32 v[132:133], v[30:31], v[130:131]
	v_pk_fma_f32 v[130:131], v[30:31], v[130:131], v[30:31] neg_lo:[1,0,0] neg_hi:[1,0,0]
	v_exp_f32_e32 v134, v134
	v_cndmask_b32_e32 v30, v130, v132, vcc
	v_cmp_gt_f32_e32 vcc, 0, v31
	v_and_b32_e32 v130, 0x7fffffff, v60
	v_exp_f32_e32 v135, v135
	v_cndmask_b32_e32 v31, v131, v133, vcc
	v_and_b32_e32 v131, 0x7fffffff, v61
	v_pk_fma_f32 v[130:131], v[130:131], s[62:63], 1.0 op_sel_hi:[1,0,0]
	v_cmp_gt_f32_e32 vcc, 0, v60
	v_rcp_f32_e32 v130, v130
	v_rcp_f32_e32 v131, v131
	s_nop 0
	v_pk_fma_f32 v[132:133], v[130:131], s[92:93], v[128:129] op_sel_hi:[1,0,0]
	s_nop 0
	v_pk_fma_f32 v[132:133], v[130:131], v[132:133], s[94:95] op_sel_hi:[1,1,0]
	s_nop 0
	v_pk_fma_f32 v[132:133], v[130:131], v[132:133], s[96:97] op_sel_hi:[1,1,0]
	s_nop 0
	v_pk_fma_f32 v[132:133], v[130:131], v[132:133], s[74:75] op_sel_hi:[1,1,0]
	s_nop 0
	v_pk_mul_f32 v[130:131], v[130:131], v[132:133]
	v_pk_mul_f32 v[132:133], v[62:63], v[62:63]
	v_pk_mul_f32 v[130:131], v[134:135], v[130:131]
	v_pk_mul_f32 v[132:133], v[132:133], s[0:1] op_sel_hi:[1,0]
	v_pk_mul_f32 v[134:135], v[60:61], v[130:131]
	v_pk_fma_f32 v[130:131], v[60:61], v[130:131], v[60:61] neg_lo:[1,0,0] neg_hi:[1,0,0]
	v_exp_f32_e32 v132, v132
	v_cndmask_b32_e32 v60, v130, v134, vcc
	v_cmp_gt_f32_e32 vcc, 0, v61
	v_and_b32_e32 v130, 0x7fffffff, v62
	v_exp_f32_e32 v133, v133
	v_cndmask_b32_e32 v61, v131, v135, vcc
	v_and_b32_e32 v131, 0x7fffffff, v63
	v_pk_fma_f32 v[130:131], v[130:131], s[62:63], 1.0 op_sel_hi:[1,0,0]
	v_cmp_gt_f32_e32 vcc, 0, v62
	v_rcp_f32_e32 v130, v130
	v_rcp_f32_e32 v131, v131
	s_nop 0
	v_pk_fma_f32 v[134:135], v[130:131], s[92:93], v[128:129] op_sel_hi:[1,0,0]
	s_nop 0
	v_pk_fma_f32 v[134:135], v[130:131], v[134:135], s[94:95] op_sel_hi:[1,1,0]
	s_nop 0
	v_pk_fma_f32 v[134:135], v[130:131], v[134:135], s[96:97] op_sel_hi:[1,1,0]
	s_nop 0
	v_pk_fma_f32 v[134:135], v[130:131], v[134:135], s[74:75] op_sel_hi:[1,1,0]
	s_nop 0
	v_pk_mul_f32 v[130:131], v[130:131], v[134:135]
	v_pk_mul_f32 v[134:135], v[72:73], v[72:73]
	v_pk_mul_f32 v[130:131], v[132:133], v[130:131]
	v_pk_mul_f32 v[134:135], v[134:135], s[0:1] op_sel_hi:[1,0]
	v_pk_mul_f32 v[132:133], v[62:63], v[130:131]
	v_pk_fma_f32 v[130:131], v[62:63], v[130:131], v[62:63] neg_lo:[1,0,0] neg_hi:[1,0,0]
	v_exp_f32_e32 v134, v134
	v_cndmask_b32_e32 v62, v130, v132, vcc
	v_cmp_gt_f32_e32 vcc, 0, v63
	v_and_b32_e32 v130, 0x7fffffff, v72
	v_exp_f32_e32 v135, v135
	v_cndmask_b32_e32 v63, v131, v133, vcc
	v_and_b32_e32 v131, 0x7fffffff, v73
	v_pk_fma_f32 v[130:131], v[130:131], s[62:63], 1.0 op_sel_hi:[1,0,0]
	v_cmp_gt_f32_e32 vcc, 0, v72
	v_rcp_f32_e32 v130, v130
	v_rcp_f32_e32 v131, v131
	s_nop 0
	v_pk_fma_f32 v[132:133], v[130:131], s[92:93], v[128:129] op_sel_hi:[1,0,0]
	s_nop 0
	v_pk_fma_f32 v[132:133], v[130:131], v[132:133], s[94:95] op_sel_hi:[1,1,0]
	s_nop 0
	v_pk_fma_f32 v[132:133], v[130:131], v[132:133], s[96:97] op_sel_hi:[1,1,0]
	s_nop 0
	v_pk_fma_f32 v[132:133], v[130:131], v[132:133], s[74:75] op_sel_hi:[1,1,0]
	s_nop 0
	v_pk_mul_f32 v[130:131], v[130:131], v[132:133]
	v_pk_mul_f32 v[132:133], v[74:75], v[74:75]
	v_pk_mul_f32 v[130:131], v[134:135], v[130:131]
	v_pk_mul_f32 v[132:133], v[132:133], s[0:1] op_sel_hi:[1,0]
	v_pk_mul_f32 v[134:135], v[72:73], v[130:131]
	v_pk_fma_f32 v[130:131], v[72:73], v[130:131], v[72:73] neg_lo:[1,0,0] neg_hi:[1,0,0]
	v_exp_f32_e32 v132, v132
	v_cndmask_b32_e32 v72, v130, v134, vcc
	v_cmp_gt_f32_e32 vcc, 0, v73
	v_and_b32_e32 v130, 0x7fffffff, v74
	v_exp_f32_e32 v133, v133
	v_cndmask_b32_e32 v73, v131, v135, vcc
	v_and_b32_e32 v131, 0x7fffffff, v75
	v_pk_fma_f32 v[130:131], v[130:131], s[62:63], 1.0 op_sel_hi:[1,0,0]
	v_cmp_gt_f32_e32 vcc, 0, v74
	v_rcp_f32_e32 v130, v130
	v_rcp_f32_e32 v131, v131
	s_nop 0
	v_pk_fma_f32 v[134:135], v[130:131], s[92:93], v[128:129] op_sel_hi:[1,0,0]
	s_nop 0
	v_pk_fma_f32 v[134:135], v[130:131], v[134:135], s[94:95] op_sel_hi:[1,1,0]
	s_nop 0
	v_pk_fma_f32 v[134:135], v[130:131], v[134:135], s[96:97] op_sel_hi:[1,1,0]
	s_nop 0
	v_pk_fma_f32 v[134:135], v[130:131], v[134:135], s[74:75] op_sel_hi:[1,1,0]
	s_nop 0
	v_pk_mul_f32 v[130:131], v[130:131], v[134:135]
	v_pk_mul_f32 v[134:135], v[104:105], v[104:105]
	v_pk_mul_f32 v[130:131], v[132:133], v[130:131]
	v_pk_mul_f32 v[134:135], v[134:135], s[0:1] op_sel_hi:[1,0]
	v_pk_mul_f32 v[132:133], v[74:75], v[130:131]
	v_pk_fma_f32 v[130:131], v[74:75], v[130:131], v[74:75] neg_lo:[1,0,0] neg_hi:[1,0,0]
	v_exp_f32_e32 v134, v134
	v_cndmask_b32_e32 v74, v130, v132, vcc
	v_cmp_gt_f32_e32 vcc, 0, v75
	v_and_b32_e32 v130, 0x7fffffff, v104
	v_exp_f32_e32 v135, v135
	v_cndmask_b32_e32 v75, v131, v133, vcc
	v_and_b32_e32 v131, 0x7fffffff, v105
	v_pk_fma_f32 v[130:131], v[130:131], s[62:63], 1.0 op_sel_hi:[1,0,0]
	v_cmp_gt_f32_e32 vcc, 0, v104
	v_rcp_f32_e32 v130, v130
	v_rcp_f32_e32 v131, v131
	s_nop 0
	v_pk_fma_f32 v[132:133], v[130:131], s[92:93], v[128:129] op_sel_hi:[1,0,0]
	s_nop 0
	v_pk_fma_f32 v[132:133], v[130:131], v[132:133], s[94:95] op_sel_hi:[1,1,0]
	s_nop 0
	v_pk_fma_f32 v[132:133], v[130:131], v[132:133], s[96:97] op_sel_hi:[1,1,0]
	s_nop 0
	v_pk_fma_f32 v[132:133], v[130:131], v[132:133], s[74:75] op_sel_hi:[1,1,0]
	s_nop 0
	v_pk_mul_f32 v[130:131], v[130:131], v[132:133]
	v_pk_mul_f32 v[132:133], v[106:107], v[106:107]
	v_pk_mul_f32 v[130:131], v[134:135], v[130:131]
	v_pk_mul_f32 v[132:133], v[132:133], s[0:1] op_sel_hi:[1,0]
	v_pk_mul_f32 v[134:135], v[104:105], v[130:131]
	v_pk_fma_f32 v[130:131], v[104:105], v[130:131], v[104:105] neg_lo:[1,0,0] neg_hi:[1,0,0]
	v_exp_f32_e32 v132, v132
	v_cndmask_b32_e32 v104, v130, v134, vcc
	v_cmp_gt_f32_e32 vcc, 0, v105
	v_and_b32_e32 v130, 0x7fffffff, v106
	v_exp_f32_e32 v133, v133
	v_cndmask_b32_e32 v105, v131, v135, vcc
	v_and_b32_e32 v131, 0x7fffffff, v107
	v_pk_fma_f32 v[130:131], v[130:131], s[62:63], 1.0 op_sel_hi:[1,0,0]
	v_cmp_gt_f32_e32 vcc, 0, v106
	v_rcp_f32_e32 v130, v130
	v_rcp_f32_e32 v131, v131
	s_nop 0
	v_pk_fma_f32 v[134:135], v[130:131], s[92:93], v[128:129] op_sel_hi:[1,0,0]
	s_nop 0
	v_pk_fma_f32 v[134:135], v[130:131], v[134:135], s[94:95] op_sel_hi:[1,1,0]
	s_nop 0
	v_pk_fma_f32 v[134:135], v[130:131], v[134:135], s[96:97] op_sel_hi:[1,1,0]
	s_nop 0
	v_pk_fma_f32 v[134:135], v[130:131], v[134:135], s[74:75] op_sel_hi:[1,1,0]
	s_nop 0
	v_pk_mul_f32 v[130:131], v[130:131], v[134:135]
	v_pk_mul_f32 v[134:135], v[68:69], v[68:69]
	v_pk_mul_f32 v[130:131], v[132:133], v[130:131]
	v_pk_mul_f32 v[134:135], v[134:135], s[0:1] op_sel_hi:[1,0]
	v_pk_mul_f32 v[132:133], v[106:107], v[130:131]
	v_pk_fma_f32 v[130:131], v[106:107], v[130:131], v[106:107] neg_lo:[1,0,0] neg_hi:[1,0,0]
	v_exp_f32_e32 v134, v134
	v_cndmask_b32_e32 v106, v130, v132, vcc
	v_cmp_gt_f32_e32 vcc, 0, v107
	v_and_b32_e32 v130, 0x7fffffff, v68
	v_exp_f32_e32 v135, v135
	v_cndmask_b32_e32 v107, v131, v133, vcc
	v_and_b32_e32 v131, 0x7fffffff, v69
	v_pk_fma_f32 v[130:131], v[130:131], s[62:63], 1.0 op_sel_hi:[1,0,0]
	v_cmp_gt_f32_e32 vcc, 0, v68
	v_rcp_f32_e32 v130, v130
	v_rcp_f32_e32 v131, v131
	s_nop 0
	v_pk_fma_f32 v[132:133], v[130:131], s[92:93], v[128:129] op_sel_hi:[1,0,0]
	s_nop 0
	v_pk_fma_f32 v[132:133], v[130:131], v[132:133], s[94:95] op_sel_hi:[1,1,0]
	s_nop 0
	v_pk_fma_f32 v[132:133], v[130:131], v[132:133], s[96:97] op_sel_hi:[1,1,0]
	s_nop 0
	v_pk_fma_f32 v[132:133], v[130:131], v[132:133], s[74:75] op_sel_hi:[1,1,0]
	s_nop 0
	v_pk_mul_f32 v[130:131], v[130:131], v[132:133]
	v_pk_mul_f32 v[132:133], v[70:71], v[70:71]
	v_pk_mul_f32 v[130:131], v[134:135], v[130:131]
	v_pk_mul_f32 v[132:133], v[132:133], s[0:1] op_sel_hi:[1,0]
	v_pk_mul_f32 v[134:135], v[68:69], v[130:131]
	v_pk_fma_f32 v[130:131], v[68:69], v[130:131], v[68:69] neg_lo:[1,0,0] neg_hi:[1,0,0]
	v_exp_f32_e32 v132, v132
	v_cndmask_b32_e32 v68, v130, v134, vcc
	v_cmp_gt_f32_e32 vcc, 0, v69
	v_and_b32_e32 v130, 0x7fffffff, v70
	v_exp_f32_e32 v133, v133
	v_cndmask_b32_e32 v69, v131, v135, vcc
	v_and_b32_e32 v131, 0x7fffffff, v71
	v_pk_fma_f32 v[130:131], v[130:131], s[62:63], 1.0 op_sel_hi:[1,0,0]
	v_cmp_gt_f32_e32 vcc, 0, v70
	v_rcp_f32_e32 v130, v130
	v_rcp_f32_e32 v131, v131
	s_nop 0
	v_pk_fma_f32 v[134:135], v[130:131], s[92:93], v[128:129] op_sel_hi:[1,0,0]
	s_nop 0
	v_pk_fma_f32 v[134:135], v[130:131], v[134:135], s[94:95] op_sel_hi:[1,1,0]
	s_nop 0
	v_pk_fma_f32 v[134:135], v[130:131], v[134:135], s[96:97] op_sel_hi:[1,1,0]
	s_nop 0
	v_pk_fma_f32 v[134:135], v[130:131], v[134:135], s[74:75] op_sel_hi:[1,1,0]
	s_nop 0
	v_pk_mul_f32 v[130:131], v[130:131], v[134:135]
	v_pk_mul_f32 v[134:135], v[100:101], v[100:101]
	v_pk_mul_f32 v[130:131], v[132:133], v[130:131]
	v_pk_mul_f32 v[134:135], v[134:135], s[0:1] op_sel_hi:[1,0]
	v_pk_mul_f32 v[132:133], v[70:71], v[130:131]
	v_pk_fma_f32 v[130:131], v[70:71], v[130:131], v[70:71] neg_lo:[1,0,0] neg_hi:[1,0,0]
	v_exp_f32_e32 v134, v134
	v_cndmask_b32_e32 v70, v130, v132, vcc
	v_cmp_gt_f32_e32 vcc, 0, v71
	v_and_b32_e32 v130, 0x7fffffff, v100
	v_exp_f32_e32 v135, v135
	v_cndmask_b32_e32 v71, v131, v133, vcc
	v_and_b32_e32 v131, 0x7fffffff, v101
	v_pk_fma_f32 v[130:131], v[130:131], s[62:63], 1.0 op_sel_hi:[1,0,0]
	v_cmp_gt_f32_e32 vcc, 0, v100
	v_rcp_f32_e32 v130, v130
	v_rcp_f32_e32 v131, v131
	s_nop 0
	v_pk_fma_f32 v[132:133], v[130:131], s[92:93], v[128:129] op_sel_hi:[1,0,0]
	s_nop 0
	v_pk_fma_f32 v[132:133], v[130:131], v[132:133], s[94:95] op_sel_hi:[1,1,0]
	s_nop 0
	v_pk_fma_f32 v[132:133], v[130:131], v[132:133], s[96:97] op_sel_hi:[1,1,0]
	s_nop 0
	v_pk_fma_f32 v[132:133], v[130:131], v[132:133], s[74:75] op_sel_hi:[1,1,0]
	s_nop 0
	v_pk_mul_f32 v[130:131], v[130:131], v[132:133]
	v_pk_mul_f32 v[132:133], v[102:103], v[102:103]
	v_pk_mul_f32 v[130:131], v[134:135], v[130:131]
	v_pk_mul_f32 v[132:133], v[132:133], s[0:1] op_sel_hi:[1,0]
	v_pk_mul_f32 v[134:135], v[100:101], v[130:131]
	v_pk_fma_f32 v[130:131], v[100:101], v[130:131], v[100:101] neg_lo:[1,0,0] neg_hi:[1,0,0]
	v_exp_f32_e32 v132, v132
	v_cndmask_b32_e32 v100, v130, v134, vcc
	v_cmp_gt_f32_e32 vcc, 0, v101
	v_and_b32_e32 v130, 0x7fffffff, v102
	v_exp_f32_e32 v133, v133
	v_cndmask_b32_e32 v101, v131, v135, vcc
	v_and_b32_e32 v131, 0x7fffffff, v103
	v_pk_fma_f32 v[130:131], v[130:131], s[62:63], 1.0 op_sel_hi:[1,0,0]
	v_cmp_gt_f32_e32 vcc, 0, v102
	v_rcp_f32_e32 v130, v130
	v_rcp_f32_e32 v131, v131
	s_nop 0
	v_pk_fma_f32 v[134:135], v[130:131], s[92:93], v[128:129] op_sel_hi:[1,0,0]
	s_nop 0
	v_pk_fma_f32 v[134:135], v[130:131], v[134:135], s[94:95] op_sel_hi:[1,1,0]
	s_nop 0
	v_pk_fma_f32 v[134:135], v[130:131], v[134:135], s[96:97] op_sel_hi:[1,1,0]
	s_nop 0
	v_pk_fma_f32 v[134:135], v[130:131], v[134:135], s[74:75] op_sel_hi:[1,1,0]
	s_nop 0
	v_pk_mul_f32 v[130:131], v[130:131], v[134:135]
	v_pk_mul_f32 v[134:135], v[64:65], v[64:65]
	v_pk_mul_f32 v[130:131], v[132:133], v[130:131]
	v_pk_mul_f32 v[134:135], v[134:135], s[0:1] op_sel_hi:[1,0]
	v_pk_mul_f32 v[132:133], v[102:103], v[130:131]
	v_pk_fma_f32 v[130:131], v[102:103], v[130:131], v[102:103] neg_lo:[1,0,0] neg_hi:[1,0,0]
	v_exp_f32_e32 v134, v134
	v_cndmask_b32_e32 v102, v130, v132, vcc
	v_cmp_gt_f32_e32 vcc, 0, v103
	v_and_b32_e32 v130, 0x7fffffff, v64
	v_exp_f32_e32 v135, v135
	v_cndmask_b32_e32 v103, v131, v133, vcc
	v_and_b32_e32 v131, 0x7fffffff, v65
	v_pk_fma_f32 v[130:131], v[130:131], s[62:63], 1.0 op_sel_hi:[1,0,0]
	v_cmp_gt_f32_e32 vcc, 0, v64
	v_rcp_f32_e32 v130, v130
	v_rcp_f32_e32 v131, v131
	s_nop 0
	v_pk_fma_f32 v[132:133], v[130:131], s[92:93], v[128:129] op_sel_hi:[1,0,0]
	s_nop 0
	v_pk_fma_f32 v[132:133], v[130:131], v[132:133], s[94:95] op_sel_hi:[1,1,0]
	s_nop 0
	v_pk_fma_f32 v[132:133], v[130:131], v[132:133], s[96:97] op_sel_hi:[1,1,0]
	s_nop 0
	v_pk_fma_f32 v[132:133], v[130:131], v[132:133], s[74:75] op_sel_hi:[1,1,0]
	s_nop 0
	v_pk_mul_f32 v[130:131], v[130:131], v[132:133]
	v_pk_mul_f32 v[132:133], v[66:67], v[66:67]
	v_pk_mul_f32 v[130:131], v[134:135], v[130:131]
	v_pk_mul_f32 v[132:133], v[132:133], s[0:1] op_sel_hi:[1,0]
	v_pk_mul_f32 v[134:135], v[64:65], v[130:131]
	v_pk_fma_f32 v[130:131], v[64:65], v[130:131], v[64:65] neg_lo:[1,0,0] neg_hi:[1,0,0]
	v_exp_f32_e32 v132, v132
	v_cndmask_b32_e32 v64, v130, v134, vcc
	v_cmp_gt_f32_e32 vcc, 0, v65
	v_and_b32_e32 v130, 0x7fffffff, v66
	v_exp_f32_e32 v133, v133
	v_cndmask_b32_e32 v65, v131, v135, vcc
	v_and_b32_e32 v131, 0x7fffffff, v67
	v_pk_fma_f32 v[130:131], v[130:131], s[62:63], 1.0 op_sel_hi:[1,0,0]
	v_cmp_gt_f32_e32 vcc, 0, v66
	v_rcp_f32_e32 v130, v130
	v_rcp_f32_e32 v131, v131
	s_nop 0
	v_pk_fma_f32 v[134:135], v[130:131], s[92:93], v[128:129] op_sel_hi:[1,0,0]
	s_nop 0
	v_pk_fma_f32 v[134:135], v[130:131], v[134:135], s[94:95] op_sel_hi:[1,1,0]
	s_nop 0
	v_pk_fma_f32 v[134:135], v[130:131], v[134:135], s[96:97] op_sel_hi:[1,1,0]
	s_nop 0
	v_pk_fma_f32 v[134:135], v[130:131], v[134:135], s[74:75] op_sel_hi:[1,1,0]
	s_nop 0
	v_pk_mul_f32 v[130:131], v[130:131], v[134:135]
	v_pk_mul_f32 v[134:135], v[96:97], v[96:97]
	v_pk_mul_f32 v[130:131], v[132:133], v[130:131]
	v_pk_mul_f32 v[134:135], v[134:135], s[0:1] op_sel_hi:[1,0]
	v_pk_mul_f32 v[132:133], v[66:67], v[130:131]
	v_pk_fma_f32 v[130:131], v[66:67], v[130:131], v[66:67] neg_lo:[1,0,0] neg_hi:[1,0,0]
	v_exp_f32_e32 v134, v134
	v_cndmask_b32_e32 v66, v130, v132, vcc
	v_cmp_gt_f32_e32 vcc, 0, v67
	v_and_b32_e32 v130, 0x7fffffff, v96
	v_exp_f32_e32 v135, v135
	v_cndmask_b32_e32 v67, v131, v133, vcc
	v_and_b32_e32 v131, 0x7fffffff, v97
	v_pk_fma_f32 v[130:131], v[130:131], s[62:63], 1.0 op_sel_hi:[1,0,0]
	v_cmp_gt_f32_e32 vcc, 0, v96
	v_rcp_f32_e32 v130, v130
	v_rcp_f32_e32 v131, v131
	s_nop 0
	v_pk_fma_f32 v[132:133], v[130:131], s[92:93], v[128:129] op_sel_hi:[1,0,0]
	s_nop 0
	v_pk_fma_f32 v[132:133], v[130:131], v[132:133], s[94:95] op_sel_hi:[1,1,0]
	s_nop 0
	v_pk_fma_f32 v[132:133], v[130:131], v[132:133], s[96:97] op_sel_hi:[1,1,0]
	s_nop 0
	v_pk_fma_f32 v[132:133], v[130:131], v[132:133], s[74:75] op_sel_hi:[1,1,0]
	s_nop 0
	v_pk_mul_f32 v[130:131], v[130:131], v[132:133]
	v_pk_mul_f32 v[132:133], v[98:99], v[98:99]
	v_pk_mul_f32 v[130:131], v[134:135], v[130:131]
	v_pk_mul_f32 v[132:133], v[132:133], s[0:1] op_sel_hi:[1,0]
	v_pk_mul_f32 v[134:135], v[96:97], v[130:131]
	v_pk_fma_f32 v[130:131], v[96:97], v[130:131], v[96:97] neg_lo:[1,0,0] neg_hi:[1,0,0]
	v_exp_f32_e32 v132, v132
	v_cndmask_b32_e32 v96, v130, v134, vcc
	v_cmp_gt_f32_e32 vcc, 0, v97
	v_and_b32_e32 v130, 0x7fffffff, v98
	v_exp_f32_e32 v133, v133
	v_cndmask_b32_e32 v97, v131, v135, vcc
	v_and_b32_e32 v131, 0x7fffffff, v99
	v_pk_fma_f32 v[130:131], v[130:131], s[62:63], 1.0 op_sel_hi:[1,0,0]
	v_cmp_gt_f32_e32 vcc, 0, v98
	v_rcp_f32_e32 v130, v130
	v_rcp_f32_e32 v131, v131
	s_nop 0
	v_pk_fma_f32 v[134:135], v[130:131], s[92:93], v[128:129] op_sel_hi:[1,0,0]
	s_nop 0
	v_pk_fma_f32 v[134:135], v[130:131], v[134:135], s[94:95] op_sel_hi:[1,1,0]
	s_nop 0
	v_pk_fma_f32 v[134:135], v[130:131], v[134:135], s[96:97] op_sel_hi:[1,1,0]
	s_nop 0
	v_pk_fma_f32 v[134:135], v[130:131], v[134:135], s[74:75] op_sel_hi:[1,1,0]
	s_nop 0
	v_pk_mul_f32 v[130:131], v[130:131], v[134:135]
	v_pk_mul_f32 v[134:135], v[92:93], v[92:93]
	v_pk_mul_f32 v[130:131], v[132:133], v[130:131]
	v_pk_mul_f32 v[134:135], v[134:135], s[0:1] op_sel_hi:[1,0]
	v_pk_mul_f32 v[132:133], v[98:99], v[130:131]
	v_pk_fma_f32 v[130:131], v[98:99], v[130:131], v[98:99] neg_lo:[1,0,0] neg_hi:[1,0,0]
	v_exp_f32_e32 v134, v134
	v_cndmask_b32_e32 v98, v130, v132, vcc
	v_cmp_gt_f32_e32 vcc, 0, v99
	v_and_b32_e32 v130, 0x7fffffff, v92
	v_exp_f32_e32 v135, v135
	v_cndmask_b32_e32 v99, v131, v133, vcc
	v_and_b32_e32 v131, 0x7fffffff, v93
	v_pk_fma_f32 v[130:131], v[130:131], s[62:63], 1.0 op_sel_hi:[1,0,0]
	v_cmp_gt_f32_e32 vcc, 0, v92
	v_rcp_f32_e32 v130, v130
	v_rcp_f32_e32 v131, v131
	s_nop 0
	v_pk_fma_f32 v[132:133], v[130:131], s[92:93], v[128:129] op_sel_hi:[1,0,0]
	s_nop 0
	v_pk_fma_f32 v[132:133], v[130:131], v[132:133], s[94:95] op_sel_hi:[1,1,0]
	s_nop 0
	v_pk_fma_f32 v[132:133], v[130:131], v[132:133], s[96:97] op_sel_hi:[1,1,0]
	s_nop 0
	v_pk_fma_f32 v[132:133], v[130:131], v[132:133], s[74:75] op_sel_hi:[1,1,0]
	s_nop 0
	v_pk_mul_f32 v[130:131], v[130:131], v[132:133]
	v_pk_mul_f32 v[132:133], v[94:95], v[94:95]
	v_pk_mul_f32 v[130:131], v[134:135], v[130:131]
	v_pk_mul_f32 v[132:133], v[132:133], s[0:1] op_sel_hi:[1,0]
	v_pk_mul_f32 v[134:135], v[92:93], v[130:131]
	v_pk_fma_f32 v[130:131], v[92:93], v[130:131], v[92:93] neg_lo:[1,0,0] neg_hi:[1,0,0]
	v_exp_f32_e32 v132, v132
	v_cndmask_b32_e32 v92, v130, v134, vcc
	v_cmp_gt_f32_e32 vcc, 0, v93
	v_and_b32_e32 v130, 0x7fffffff, v94
	v_exp_f32_e32 v133, v133
	v_cndmask_b32_e32 v93, v131, v135, vcc
	v_and_b32_e32 v131, 0x7fffffff, v95
	v_pk_fma_f32 v[130:131], v[130:131], s[62:63], 1.0 op_sel_hi:[1,0,0]
	v_cmp_gt_f32_e32 vcc, 0, v94
	v_rcp_f32_e32 v130, v130
	v_rcp_f32_e32 v131, v131
	s_nop 0
	v_pk_fma_f32 v[134:135], v[130:131], s[92:93], v[128:129] op_sel_hi:[1,0,0]
	s_nop 0
	v_pk_fma_f32 v[134:135], v[130:131], v[134:135], s[94:95] op_sel_hi:[1,1,0]
	s_nop 0
	v_pk_fma_f32 v[134:135], v[130:131], v[134:135], s[96:97] op_sel_hi:[1,1,0]
	s_nop 0
	v_pk_fma_f32 v[134:135], v[130:131], v[134:135], s[74:75] op_sel_hi:[1,1,0]
	s_nop 0
	v_pk_mul_f32 v[130:131], v[130:131], v[134:135]
	v_pk_mul_f32 v[134:135], v[124:125], v[124:125]
	v_pk_mul_f32 v[130:131], v[132:133], v[130:131]
	v_pk_mul_f32 v[134:135], v[134:135], s[0:1] op_sel_hi:[1,0]
	v_pk_mul_f32 v[132:133], v[94:95], v[130:131]
	v_pk_fma_f32 v[130:131], v[94:95], v[130:131], v[94:95] neg_lo:[1,0,0] neg_hi:[1,0,0]
	v_exp_f32_e32 v134, v134
	v_cndmask_b32_e32 v94, v130, v132, vcc
	v_cmp_gt_f32_e32 vcc, 0, v95
	v_and_b32_e32 v130, 0x7fffffff, v124
	v_exp_f32_e32 v135, v135
	v_cndmask_b32_e32 v95, v131, v133, vcc
	v_and_b32_e32 v131, 0x7fffffff, v125
	v_pk_fma_f32 v[130:131], v[130:131], s[62:63], 1.0 op_sel_hi:[1,0,0]
	v_cmp_gt_f32_e32 vcc, 0, v124
	v_rcp_f32_e32 v130, v130
	v_rcp_f32_e32 v131, v131
	s_nop 0
	v_pk_fma_f32 v[132:133], v[130:131], s[92:93], v[128:129] op_sel_hi:[1,0,0]
	s_nop 0
	v_pk_fma_f32 v[132:133], v[130:131], v[132:133], s[94:95] op_sel_hi:[1,1,0]
	s_nop 0
	v_pk_fma_f32 v[132:133], v[130:131], v[132:133], s[96:97] op_sel_hi:[1,1,0]
	s_nop 0
	v_pk_fma_f32 v[132:133], v[130:131], v[132:133], s[74:75] op_sel_hi:[1,1,0]
	s_nop 0
	v_pk_mul_f32 v[130:131], v[130:131], v[132:133]
	v_pk_mul_f32 v[132:133], v[126:127], v[126:127]
	v_pk_mul_f32 v[130:131], v[134:135], v[130:131]
	s_nop 0
	v_pk_mul_f32 v[134:135], v[124:125], v[130:131]
	v_pk_fma_f32 v[130:131], v[124:125], v[130:131], v[124:125] neg_lo:[1,0,0] neg_hi:[1,0,0]
	s_nop 0
	v_cndmask_b32_e32 v124, v130, v134, vcc
	v_cmp_gt_f32_e32 vcc, 0, v125
	v_and_b32_e32 v130, 0x7fffffff, v126
	s_nop 0
	v_cndmask_b32_e32 v125, v131, v135, vcc
	v_and_b32_e32 v131, 0x7fffffff, v127
	v_pk_fma_f32 v[130:131], v[130:131], s[62:63], 1.0 op_sel_hi:[1,0,0]
	v_cmp_gt_f32_e32 vcc, 0, v126
	v_rcp_f32_e32 v130, v130
	v_rcp_f32_e32 v131, v131
	s_nop 0
	v_pk_fma_f32 v[128:129], v[130:131], s[92:93], v[128:129] op_sel_hi:[1,0,0]
	s_nop 0
	v_pk_fma_f32 v[128:129], v[130:131], v[128:129], s[94:95] op_sel_hi:[1,1,0]
	s_nop 0
	v_pk_fma_f32 v[128:129], v[130:131], v[128:129], s[96:97] op_sel_hi:[1,1,0]
	s_nop 0
	v_pk_fma_f32 v[128:129], v[130:131], v[128:129], s[74:75] op_sel_hi:[1,1,0]
	s_nop 0
	v_pk_mul_f32 v[128:129], v[130:131], v[128:129]
	v_pk_mul_f32 v[130:131], v[132:133], s[0:1] op_sel_hi:[1,0]
	s_nop 0
	v_exp_f32_e32 v130, v130
	v_exp_f32_e32 v131, v131
	s_nop 0
	v_pk_mul_f32 v[128:129], v[130:131], v[128:129]
	s_nop 0
	v_pk_mul_f32 v[130:131], v[126:127], v[128:129]
	v_pk_fma_f32 v[128:129], v[126:127], v[128:129], v[126:127] neg_lo:[1,0,0] neg_hi:[1,0,0]
	s_nop 0
	v_cndmask_b32_e32 v126, v128, v130, vcc
	v_cmp_gt_f32_e32 vcc, 0, v127
	s_nop 1
	v_cndmask_b32_e32 v127, v129, v131, vcc
